# GEMM k-loops (MLP1, MLP2, AQKV, CIN, A-out, C-out) rewritten by hand: LDS-DMA global->LDS staging (source-side swizzle), double-buffered fragment reads one k-step ahead, one barrier per k-tile; same b
# speedup vs baseline: 1.0913x; 1.0778x over previous
.LBB0_178:
	s_or_b64 exec, exec, s[10:11]
	v_readlane_b32 s12, v250, 9
	v_readlane_b32 s14, v250, 11
	v_readlane_b32 s15, v250, 12
	s_add_u32 s8, s14, s8
	s_addc_u32 s9, s15, s9
	s_add_u32 s10, s14, s0
	v_mov_b32_e32 v98, 0
	s_addc_u32 s11, s15, s1
	s_mov_b32 s3, 0
	v_add_u32_e32 v176, 0x18000, v174
	v_mov_b32_e32 v99, v98
	v_mov_b32_e32 v100, v98
	v_mov_b32_e32 v101, v98
	v_mov_b32_e32 v102, v98
	v_mov_b32_e32 v103, v98
	v_mov_b32_e32 v104, v98
	v_mov_b32_e32 v105, v98
	v_mov_b32_e32 v106, v98
	v_mov_b32_e32 v107, v98
	v_mov_b32_e32 v108, v98
	v_mov_b32_e32 v109, v98
	v_mov_b32_e32 v110, v98
	v_mov_b32_e32 v111, v98
	v_mov_b32_e32 v112, v98
	v_mov_b32_e32 v113, v98
	v_mov_b32_e32 v66, v98
	v_mov_b32_e32 v67, v98
	v_mov_b32_e32 v68, v98
	v_mov_b32_e32 v69, v98
	v_mov_b32_e32 v70, v98
	v_mov_b32_e32 v71, v98
	v_mov_b32_e32 v72, v98
	v_mov_b32_e32 v73, v98
	v_mov_b32_e32 v74, v98
	v_mov_b32_e32 v75, v98
	v_mov_b32_e32 v76, v98
	v_mov_b32_e32 v77, v98
	v_mov_b32_e32 v78, v98
	v_mov_b32_e32 v79, v98
	v_mov_b32_e32 v80, v98
	v_mov_b32_e32 v81, v98
	v_mov_b32_e32 v34, v98
	v_mov_b32_e32 v35, v98
	v_mov_b32_e32 v36, v98
	v_mov_b32_e32 v37, v98
	v_mov_b32_e32 v38, v98
	v_mov_b32_e32 v39, v98
	v_mov_b32_e32 v40, v98
	v_mov_b32_e32 v41, v98
	v_mov_b32_e32 v42, v98
	v_mov_b32_e32 v43, v98
	v_mov_b32_e32 v44, v98
	v_mov_b32_e32 v45, v98
	v_mov_b32_e32 v46, v98
	v_mov_b32_e32 v47, v98
	v_mov_b32_e32 v48, v98
	v_mov_b32_e32 v49, v98
	v_mov_b32_e32 v2, v98
	v_mov_b32_e32 v3, v98
	v_mov_b32_e32 v4, v98
	v_mov_b32_e32 v5, v98
	v_mov_b32_e32 v6, v98
	v_mov_b32_e32 v7, v98
	v_mov_b32_e32 v8, v98
	v_mov_b32_e32 v9, v98
	v_mov_b32_e32 v10, v98
	v_mov_b32_e32 v11, v98
	v_mov_b32_e32 v12, v98
	v_mov_b32_e32 v13, v98
	v_mov_b32_e32 v14, v98
	v_mov_b32_e32 v15, v98
	v_mov_b32_e32 v16, v98
	v_mov_b32_e32 v17, v98
	v_mov_b32_e32 v114, v98
	v_mov_b32_e32 v115, v98
	v_mov_b32_e32 v116, v98
	v_mov_b32_e32 v117, v98
	v_mov_b32_e32 v118, v98
	v_mov_b32_e32 v119, v98
	v_mov_b32_e32 v120, v98
	v_mov_b32_e32 v121, v98
	v_mov_b32_e32 v122, v98
	v_mov_b32_e32 v123, v98
	v_mov_b32_e32 v124, v98
	v_mov_b32_e32 v125, v98
	v_mov_b32_e32 v126, v98
	v_mov_b32_e32 v127, v98
	v_mov_b32_e32 v128, v98
	v_mov_b32_e32 v129, v98
	v_mov_b32_e32 v82, v98
	v_mov_b32_e32 v83, v98
	v_mov_b32_e32 v84, v98
	v_mov_b32_e32 v85, v98
	v_mov_b32_e32 v86, v98
	v_mov_b32_e32 v87, v98
	v_mov_b32_e32 v88, v98
	v_mov_b32_e32 v89, v98
	v_mov_b32_e32 v90, v98
	v_mov_b32_e32 v91, v98
	v_mov_b32_e32 v92, v98
	v_mov_b32_e32 v93, v98
	v_mov_b32_e32 v94, v98
	v_mov_b32_e32 v95, v98
	v_mov_b32_e32 v96, v98
	v_mov_b32_e32 v97, v98
	v_mov_b32_e32 v50, v98
	v_mov_b32_e32 v51, v98
	v_mov_b32_e32 v52, v98
	v_mov_b32_e32 v53, v98
	v_mov_b32_e32 v54, v98
	v_mov_b32_e32 v55, v98
	v_mov_b32_e32 v56, v98
	v_mov_b32_e32 v57, v98
	v_mov_b32_e32 v58, v98
	v_mov_b32_e32 v59, v98
	v_mov_b32_e32 v60, v98
	v_mov_b32_e32 v61, v98
	v_mov_b32_e32 v62, v98
	v_mov_b32_e32 v63, v98
	v_mov_b32_e32 v64, v98
	v_mov_b32_e32 v65, v98
	v_mov_b32_e32 v18, v98
	v_mov_b32_e32 v19, v98
	v_mov_b32_e32 v20, v98
	v_mov_b32_e32 v21, v98
	v_mov_b32_e32 v22, v98
	v_mov_b32_e32 v23, v98
	v_mov_b32_e32 v24, v98
	v_mov_b32_e32 v25, v98
	v_mov_b32_e32 v26, v98
	v_mov_b32_e32 v27, v98
	v_mov_b32_e32 v28, v98
	v_mov_b32_e32 v29, v98
	v_mov_b32_e32 v30, v98
	v_mov_b32_e32 v31, v98
	v_mov_b32_e32 v32, v98
	v_mov_b32_e32 v33, v98
	v_readlane_b32 s13, v250, 10
	s_add_u32 s18, s8, 0x5800080
	s_addc_u32 s19, s9, 0
	s_add_u32 s20, s18, 0x20000
	s_addc_u32 s21, s19, 0
	s_add_u32 s22, s18, 0x40000
	s_addc_u32 s23, s19, 0
	s_add_u32 s24, s18, 0x60000
	s_addc_u32 s25, s19, 0
	s_add_u32 s8, s10, 0x5100080
	s_addc_u32 s9, s11, 0
	s_add_u32 s10, s8, 0x20000
	s_addc_u32 s11, s9, 0
	s_add_u32 s12, s8, 0x40000
	s_addc_u32 s13, s9, 0
	s_add_u32 s14, s8, 0x60000
	s_addc_u32 s15, s9, 0
	v_lshrrev_b32_e32 v170, 3, v204
	v_lshrrev_b32_e32 v171, 4, v204
	v_xor_b32_e32 v171, v171, v204
	v_and_b32_e32 v171, 7, v171
	v_lshlrev_b32_e32 v171, 4, v171
	v_lshl_or_b32 v170, v170, 11, v171
	v_readfirstlane_b32 s26, v204
	s_and_b32 s26, s26, 0x3c0
	s_lshl_b32 s26, s26, 4
	s_mov_b32 s3, 0
	ds_read_b128 v[130:133], v225
	ds_read_b128 v[138:141], v226
	ds_read_b128 v[134:137], v225 offset:4096
	ds_read_b128 v[142:145], v226 offset:4096
	ds_read_b128 v[146:149], v226 offset:8192
	ds_read_b128 v[150:153], v226 offset:12288
	s_add_u32 m0, s26, 0x8000
	s_nop 0
	global_load_lds_dwordx4 v170, s[8:9]
	s_add_u32 m0, s26, 0x18000
	s_nop 0
	global_load_lds_dwordx4 v170, s[18:19]
	s_add_u32 m0, s26, 0xa000
	s_nop 0
	global_load_lds_dwordx4 v170, s[10:11]
	s_add_u32 m0, s26, 0x1a000
	s_nop 0
	global_load_lds_dwordx4 v170, s[20:21]
	s_add_u32 m0, s26, 0xc000
	s_nop 0
	global_load_lds_dwordx4 v170, s[12:13]
	s_add_u32 m0, s26, 0x1c000
	s_nop 0
	global_load_lds_dwordx4 v170, s[22:23]
	s_add_u32 m0, s26, 0xe000
	s_nop 0
	global_load_lds_dwordx4 v170, s[14:15]
	s_add_u32 m0, s26, 0x1e000
	s_nop 0
	global_load_lds_dwordx4 v170, s[24:25]
	s_branch .Lg_cin_mid
.Lg_cin_top:
	ds_read_b128 v[130:133], v225
	ds_read_b128 v[138:141], v226
	ds_read_b128 v[134:137], v225 offset:4096
	ds_read_b128 v[142:145], v226 offset:4096
	ds_read_b128 v[146:149], v226 offset:8192
	ds_read_b128 v[150:153], v226 offset:12288
	s_add_u32 m0, s26, 0x8000
	v_mfma_f32_32x32x16_bf16 v[98:113], v[154:157], v[162:165], v[98:113]
	global_load_lds_dwordx4 v170, s[8:9]
	s_add_u32 m0, s26, 0x18000
	v_mfma_f32_32x32x16_bf16 v[114:129], v[158:161], v[162:165], v[114:129]
	global_load_lds_dwordx4 v170, s[18:19]
	s_add_u32 m0, s26, 0xa000
	v_mfma_f32_32x32x16_bf16 v[66:81], v[154:157], v[166:169], v[66:81]
	global_load_lds_dwordx4 v170, s[10:11]
	s_add_u32 m0, s26, 0x1a000
	v_mfma_f32_32x32x16_bf16 v[82:97], v[158:161], v[166:169], v[82:97]
	global_load_lds_dwordx4 v170, s[20:21]
	s_add_u32 m0, s26, 0xc000
	v_mfma_f32_32x32x16_bf16 v[34:49], v[154:157], v[178:181], v[34:49]
	global_load_lds_dwordx4 v170, s[12:13]
	s_add_u32 m0, s26, 0x1c000
	v_mfma_f32_32x32x16_bf16 v[50:65], v[158:161], v[178:181], v[50:65]
	global_load_lds_dwordx4 v170, s[22:23]
	s_add_u32 m0, s26, 0xe000
	v_mfma_f32_32x32x16_bf16 v[2:17], v[154:157], v[182:185], v[2:17]
	global_load_lds_dwordx4 v170, s[14:15]
	s_add_u32 m0, s26, 0x1e000
	v_mfma_f32_32x32x16_bf16 v[18:33], v[158:161], v[182:185], v[18:33]
	global_load_lds_dwordx4 v170, s[24:25]
.Lg_cin_mid:
	ds_read_b128 v[154:157], v227
	ds_read_b128 v[162:165], v228
	ds_read_b128 v[158:161], v227 offset:4096
	ds_read_b128 v[166:169], v228 offset:4096
	ds_read_b128 v[178:181], v228 offset:8192
	ds_read_b128 v[182:185], v228 offset:12288
	s_waitcnt lgkmcnt(6)
	v_mfma_f32_32x32x16_bf16 v[98:113], v[130:133], v[138:141], v[98:113]
	s_add_u32 s8, s8, 0x80
	s_addc_u32 s9, s9, 0
	v_mfma_f32_32x32x16_bf16 v[114:129], v[134:137], v[138:141], v[114:129]
	s_add_u32 s10, s10, 0x80
	s_addc_u32 s11, s11, 0
	v_mfma_f32_32x32x16_bf16 v[66:81], v[130:133], v[142:145], v[66:81]
	s_add_u32 s12, s12, 0x80
	s_addc_u32 s13, s13, 0
	v_mfma_f32_32x32x16_bf16 v[82:97], v[134:137], v[142:145], v[82:97]
	s_add_u32 s14, s14, 0x80
	s_addc_u32 s15, s15, 0
	v_mfma_f32_32x32x16_bf16 v[34:49], v[130:133], v[146:149], v[34:49]
	s_add_u32 s18, s18, 0x80
	s_addc_u32 s19, s19, 0
	v_mfma_f32_32x32x16_bf16 v[50:65], v[134:137], v[146:149], v[50:65]
	s_add_u32 s20, s20, 0x80
	s_addc_u32 s21, s21, 0
	v_mfma_f32_32x32x16_bf16 v[2:17], v[130:133], v[150:153], v[2:17]
	s_add_u32 s22, s22, 0x80
	s_addc_u32 s23, s23, 0
	v_mfma_f32_32x32x16_bf16 v[18:33], v[134:137], v[150:153], v[18:33]
	s_add_u32 s24, s24, 0x80
	s_addc_u32 s25, s25, 0
	ds_read_b128 v[130:133], v229
	ds_read_b128 v[138:141], v230
	ds_read_b128 v[134:137], v229 offset:4096
	ds_read_b128 v[142:145], v230 offset:4096
	ds_read_b128 v[146:149], v230 offset:8192
	ds_read_b128 v[150:153], v230 offset:12288
	s_waitcnt lgkmcnt(6)
	v_mfma_f32_32x32x16_bf16 v[98:113], v[154:157], v[162:165], v[98:113]
	v_mfma_f32_32x32x16_bf16 v[114:129], v[158:161], v[162:165], v[114:129]
	v_mfma_f32_32x32x16_bf16 v[66:81], v[154:157], v[166:169], v[66:81]
	v_mfma_f32_32x32x16_bf16 v[82:97], v[158:161], v[166:169], v[82:97]
	v_mfma_f32_32x32x16_bf16 v[34:49], v[154:157], v[178:181], v[34:49]
	v_mfma_f32_32x32x16_bf16 v[50:65], v[158:161], v[178:181], v[50:65]
	v_mfma_f32_32x32x16_bf16 v[2:17], v[154:157], v[182:185], v[2:17]
	v_mfma_f32_32x32x16_bf16 v[18:33], v[158:161], v[182:185], v[18:33]
	ds_read_b128 v[154:157], v231
	ds_read_b128 v[162:165], v232
	ds_read_b128 v[158:161], v231 offset:4096
	ds_read_b128 v[166:169], v232 offset:4096
	ds_read_b128 v[178:181], v232 offset:8192
	ds_read_b128 v[182:185], v232 offset:12288
	s_waitcnt lgkmcnt(6)
	v_mfma_f32_32x32x16_bf16 v[98:113], v[130:133], v[138:141], v[98:113]
	v_mfma_f32_32x32x16_bf16 v[114:129], v[134:137], v[138:141], v[114:129]
	v_mfma_f32_32x32x16_bf16 v[66:81], v[130:133], v[142:145], v[66:81]
	v_mfma_f32_32x32x16_bf16 v[82:97], v[134:137], v[142:145], v[82:97]
	v_mfma_f32_32x32x16_bf16 v[34:49], v[130:133], v[146:149], v[34:49]
	v_mfma_f32_32x32x16_bf16 v[50:65], v[134:137], v[146:149], v[50:65]
	v_mfma_f32_32x32x16_bf16 v[2:17], v[130:133], v[150:153], v[2:17]
	v_mfma_f32_32x32x16_bf16 v[18:33], v[134:137], v[150:153], v[18:33]
	s_waitcnt vmcnt(0) lgkmcnt(0)
	s_barrier
	ds_read_b128 v[130:133], v225 offset:32768
	ds_read_b128 v[138:141], v234
	ds_read_b128 v[134:137], v225 offset:36864
	ds_read_b128 v[142:145], v234 offset:4096
	ds_read_b128 v[146:149], v234 offset:8192
	ds_read_b128 v[150:153], v234 offset:12288
	s_cmp_ge_u32 s3, 14
	s_cbranch_scc1 .Lg_cin_nodma
	s_add_u32 m0, s26, 0x0
	v_mfma_f32_32x32x16_bf16 v[98:113], v[154:157], v[162:165], v[98:113]
	global_load_lds_dwordx4 v170, s[8:9]
	s_add_u32 m0, s26, 0x10000
	v_mfma_f32_32x32x16_bf16 v[114:129], v[158:161], v[162:165], v[114:129]
	global_load_lds_dwordx4 v170, s[18:19]
	s_add_u32 m0, s26, 0x2000
	v_mfma_f32_32x32x16_bf16 v[66:81], v[154:157], v[166:169], v[66:81]
	global_load_lds_dwordx4 v170, s[10:11]
	s_add_u32 m0, s26, 0x12000
	v_mfma_f32_32x32x16_bf16 v[82:97], v[158:161], v[166:169], v[82:97]
	global_load_lds_dwordx4 v170, s[20:21]
	s_add_u32 m0, s26, 0x4000
	v_mfma_f32_32x32x16_bf16 v[34:49], v[154:157], v[178:181], v[34:49]
	global_load_lds_dwordx4 v170, s[12:13]
	s_add_u32 m0, s26, 0x14000
	v_mfma_f32_32x32x16_bf16 v[50:65], v[158:161], v[178:181], v[50:65]
	global_load_lds_dwordx4 v170, s[22:23]
	s_add_u32 m0, s26, 0x6000
	v_mfma_f32_32x32x16_bf16 v[2:17], v[154:157], v[182:185], v[2:17]
	global_load_lds_dwordx4 v170, s[14:15]
	s_add_u32 m0, s26, 0x16000
	v_mfma_f32_32x32x16_bf16 v[18:33], v[158:161], v[182:185], v[18:33]
	global_load_lds_dwordx4 v170, s[24:25]
	s_branch .Lg_cin_join
.Lg_cin_nodma:
	v_mfma_f32_32x32x16_bf16 v[98:113], v[154:157], v[162:165], v[98:113]
	v_mfma_f32_32x32x16_bf16 v[114:129], v[158:161], v[162:165], v[114:129]
	v_mfma_f32_32x32x16_bf16 v[66:81], v[154:157], v[166:169], v[66:81]
	v_mfma_f32_32x32x16_bf16 v[82:97], v[158:161], v[166:169], v[82:97]
	v_mfma_f32_32x32x16_bf16 v[34:49], v[154:157], v[178:181], v[34:49]
	v_mfma_f32_32x32x16_bf16 v[50:65], v[158:161], v[178:181], v[50:65]
	v_mfma_f32_32x32x16_bf16 v[2:17], v[154:157], v[182:185], v[2:17]
	v_mfma_f32_32x32x16_bf16 v[18:33], v[158:161], v[182:185], v[18:33]
.Lg_cin_join:
	ds_read_b128 v[154:157], v227 offset:32768
	ds_read_b128 v[162:165], v235
	ds_read_b128 v[158:161], v227 offset:36864
	ds_read_b128 v[166:169], v235 offset:4096
	ds_read_b128 v[178:181], v235 offset:8192
	ds_read_b128 v[182:185], v235 offset:12288
	s_waitcnt lgkmcnt(6)
	v_mfma_f32_32x32x16_bf16 v[98:113], v[130:133], v[138:141], v[98:113]
	s_add_u32 s8, s8, 0x80
	s_addc_u32 s9, s9, 0
	v_mfma_f32_32x32x16_bf16 v[114:129], v[134:137], v[138:141], v[114:129]
	s_add_u32 s10, s10, 0x80
	s_addc_u32 s11, s11, 0
	v_mfma_f32_32x32x16_bf16 v[66:81], v[130:133], v[142:145], v[66:81]
	s_add_u32 s12, s12, 0x80
	s_addc_u32 s13, s13, 0
	v_mfma_f32_32x32x16_bf16 v[82:97], v[134:137], v[142:145], v[82:97]
	s_add_u32 s14, s14, 0x80
	s_addc_u32 s15, s15, 0
	v_mfma_f32_32x32x16_bf16 v[34:49], v[130:133], v[146:149], v[34:49]
	s_add_u32 s18, s18, 0x80
	s_addc_u32 s19, s19, 0
	v_mfma_f32_32x32x16_bf16 v[50:65], v[134:137], v[146:149], v[50:65]
	s_add_u32 s20, s20, 0x80
	s_addc_u32 s21, s21, 0
	v_mfma_f32_32x32x16_bf16 v[2:17], v[130:133], v[150:153], v[2:17]
	s_add_u32 s22, s22, 0x80
	s_addc_u32 s23, s23, 0
	v_mfma_f32_32x32x16_bf16 v[18:33], v[134:137], v[150:153], v[18:33]
	s_add_u32 s24, s24, 0x80
	s_addc_u32 s25, s25, 0
	ds_read_b128 v[130:133], v229 offset:32768
	ds_read_b128 v[138:141], v236
	ds_read_b128 v[134:137], v229 offset:36864
	ds_read_b128 v[142:145], v236 offset:4096
	ds_read_b128 v[146:149], v236 offset:8192
	ds_read_b128 v[150:153], v236 offset:12288
	s_waitcnt lgkmcnt(6)
	v_mfma_f32_32x32x16_bf16 v[98:113], v[154:157], v[162:165], v[98:113]
	v_mfma_f32_32x32x16_bf16 v[114:129], v[158:161], v[162:165], v[114:129]
	v_mfma_f32_32x32x16_bf16 v[66:81], v[154:157], v[166:169], v[66:81]
	v_mfma_f32_32x32x16_bf16 v[82:97], v[158:161], v[166:169], v[82:97]
	v_mfma_f32_32x32x16_bf16 v[34:49], v[154:157], v[178:181], v[34:49]
	v_mfma_f32_32x32x16_bf16 v[50:65], v[158:161], v[178:181], v[50:65]
	v_mfma_f32_32x32x16_bf16 v[2:17], v[154:157], v[182:185], v[2:17]
	v_mfma_f32_32x32x16_bf16 v[18:33], v[158:161], v[182:185], v[18:33]
	ds_read_b128 v[154:157], v231 offset:32768
	ds_read_b128 v[162:165], v237
	ds_read_b128 v[158:161], v231 offset:36864
	ds_read_b128 v[166:169], v237 offset:4096
	ds_read_b128 v[178:181], v237 offset:8192
	ds_read_b128 v[182:185], v237 offset:12288
	s_waitcnt lgkmcnt(6)
	v_mfma_f32_32x32x16_bf16 v[98:113], v[130:133], v[138:141], v[98:113]
	v_mfma_f32_32x32x16_bf16 v[114:129], v[134:137], v[138:141], v[114:129]
	v_mfma_f32_32x32x16_bf16 v[66:81], v[130:133], v[142:145], v[66:81]
	v_mfma_f32_32x32x16_bf16 v[82:97], v[134:137], v[142:145], v[82:97]
	v_mfma_f32_32x32x16_bf16 v[34:49], v[130:133], v[146:149], v[34:49]
	v_mfma_f32_32x32x16_bf16 v[50:65], v[134:137], v[146:149], v[50:65]
	v_mfma_f32_32x32x16_bf16 v[2:17], v[130:133], v[150:153], v[2:17]
	v_mfma_f32_32x32x16_bf16 v[18:33], v[134:137], v[150:153], v[18:33]
	s_waitcnt vmcnt(0) lgkmcnt(0)
	s_barrier
	s_add_i32 s3, s3, 2
	s_cmp_lt_u32 s3, 16
	s_cbranch_scc1 .Lg_cin_top
	v_mfma_f32_32x32x16_bf16 v[98:113], v[154:157], v[162:165], v[98:113]
	v_mfma_f32_32x32x16_bf16 v[114:129], v[158:161], v[162:165], v[114:129]
	v_mfma_f32_32x32x16_bf16 v[66:81], v[154:157], v[166:169], v[66:81]
	v_mfma_f32_32x32x16_bf16 v[82:97], v[158:161], v[166:169], v[82:97]
	v_mfma_f32_32x32x16_bf16 v[34:49], v[154:157], v[178:181], v[34:49]
	v_mfma_f32_32x32x16_bf16 v[50:65], v[158:161], v[178:181], v[50:65]
	v_mfma_f32_32x32x16_bf16 v[2:17], v[154:157], v[182:185], v[2:17]
	v_mfma_f32_32x32x16_bf16 v[18:33], v[158:161], v[182:185], v[18:33]
	s_nop 7
	s_nop 7
	s_branch .LBB0_196

.LBB0_1123:
	s_bfe_u32 s4, s14, 0x20003
	s_lshr_b32 s0, s14, 5
	s_lshl_b32 s0, s0, 3
	s_and_b32 s1, s14, 7
	s_add_i32 s0, s0, s1
	s_lshl_b32 s2, s0, 8
	s_ashr_i32 s3, s2, 31
	s_ashr_i32 s5, s4, 31
	s_lshl_b64 s[0:1], s[4:5], 19
	s_lshl_b64 s[6:7], s[2:3], 11
	v_readlane_b32 s8, v252, 31
	v_readlane_b32 s9, v252, 32
	s_add_u32 s8, s8, s6
	v_mov_b32_e32 v34, v178
	s_addc_u32 s9, s9, s7
	v_readlane_b32 s3, v252, 49
	s_add_u32 s10, s3, s0
	v_lshlrev_b32_e32 v0, 4, v34
	v_readlane_b32 s3, v252, 50
	v_ashrrev_i32_e32 v35, 3, v34
	v_and_b32_e32 v0, 0x70, v0
	s_addc_u32 s11, s3, s1
	v_lshl_or_b32 v0, v35, 11, v0
	v_lshl_add_u64 v[26:27], s[10:11], 0, v[0:1]
	v_add_co_u32_e32 v10, vcc, s52, v26
	v_lshl_add_u64 v[28:29], s[8:9], 0, v[0:1]
	s_nop 0
	v_addc_co_u32_e32 v11, vcc, 0, v27, vcc
	v_add_co_u32_e32 v14, vcc, s52, v28
	global_load_dwordx4 v[2:5], v0, s[10:11]
	global_load_dwordx4 v[6:9], v0, s[8:9]
	v_addc_co_u32_e32 v15, vcc, 0, v29, vcc
	v_add_co_u32_e32 v18, vcc, s56, v26
	global_load_dwordx4 v[10:13], v[10:11], off
	s_nop 0
	global_load_dwordx4 v[14:17], v[14:15], off
	v_addc_co_u32_e32 v19, vcc, 0, v27, vcc
	v_add_co_u32_e32 v22, vcc, s56, v28
	v_readlane_b32 s8, v250, 9
	s_nop 0
	v_addc_co_u32_e32 v23, vcc, 0, v29, vcc
	v_add_co_u32_e32 v26, vcc, s57, v26
	global_load_dwordx4 v[18:21], v[18:19], off
	s_nop 0
	global_load_dwordx4 v[22:25], v[22:23], off
	v_addc_co_u32_e32 v27, vcc, 0, v27, vcc
	v_add_co_u32_e32 v30, vcc, s57, v28
	v_lshrrev_b32_e32 v36, 1, v35
	s_nop 0
	v_addc_co_u32_e32 v31, vcc, 0, v29, vcc
	global_load_dwordx4 v[26:29], v[26:27], off
	s_nop 0
	global_load_dwordx4 v[30:33], v[30:31], off
	v_readlane_b32 s10, v250, 11
	v_xor_b32_e32 v34, v36, v34
	v_readlane_b32 s11, v250, 12
	s_add_u32 s6, s10, s6
	v_lshlrev_b32_e32 v35, 7, v35
	v_lshlrev_b32_e32 v34, 4, v34
	s_addc_u32 s7, s11, s7
	v_mov_b32_e32 v82, 0
	v_and_or_b32 v198, v34, s55, v35
	v_readlane_b32 s9, v250, 10
	s_add_u32 s8, s10, s0
	s_mov_b32 s3, 0
	v_mov_b32_e32 v83, v82
	v_mov_b32_e32 v84, v82
	v_mov_b32_e32 v85, v82
	v_mov_b32_e32 v86, v82
	v_mov_b32_e32 v87, v82
	v_mov_b32_e32 v88, v82
	v_mov_b32_e32 v89, v82
	v_mov_b32_e32 v90, v82
	v_mov_b32_e32 v91, v82
	v_mov_b32_e32 v92, v82
	v_mov_b32_e32 v93, v82
	v_mov_b32_e32 v94, v82
	v_mov_b32_e32 v95, v82
	v_mov_b32_e32 v96, v82
	v_mov_b32_e32 v97, v82
	v_mov_b32_e32 v66, v82
	v_add_u32_e32 v199, 0x10000, v198
	s_addc_u32 s9, s11, s1
	v_mov_b32_e32 v67, v82
	v_mov_b32_e32 v68, v82
	v_mov_b32_e32 v69, v82
	v_mov_b32_e32 v70, v82
	v_mov_b32_e32 v71, v82
	v_mov_b32_e32 v72, v82
	v_mov_b32_e32 v73, v82
	v_mov_b32_e32 v74, v82
	v_mov_b32_e32 v75, v82
	v_mov_b32_e32 v76, v82
	v_mov_b32_e32 v77, v82
	v_mov_b32_e32 v78, v82
	v_mov_b32_e32 v79, v82
	v_mov_b32_e32 v80, v82
	v_mov_b32_e32 v81, v82
	v_mov_b32_e32 v114, v82
	v_mov_b32_e32 v115, v82
	s_waitcnt vmcnt(7)
	ds_write_b128 v198, v[2:5]
	s_waitcnt vmcnt(6)
	ds_write_b128 v199, v[6:9]
	s_waitcnt vmcnt(5)
	ds_write_b128 v198, v[10:13] offset:8192
	s_waitcnt vmcnt(4)
	ds_write_b128 v199, v[14:17] offset:8192
	s_waitcnt vmcnt(3)
	ds_write_b128 v198, v[18:21] offset:16384
	s_waitcnt vmcnt(2)
	ds_write_b128 v199, v[22:25] offset:16384
	s_waitcnt vmcnt(1)
	ds_write_b128 v198, v[26:29] offset:24576
	s_waitcnt vmcnt(0)
	ds_write_b128 v199, v[30:33] offset:24576
	v_mov_b32_e32 v18, v82
	v_mov_b32_e32 v19, v82
	v_mov_b32_e32 v20, v82
	v_mov_b32_e32 v21, v82
	v_mov_b32_e32 v22, v82
	v_mov_b32_e32 v23, v82
	v_mov_b32_e32 v24, v82
	v_mov_b32_e32 v25, v82
	v_mov_b32_e32 v26, v82
	v_mov_b32_e32 v27, v82
	v_mov_b32_e32 v28, v82
	v_mov_b32_e32 v29, v82
	v_mov_b32_e32 v30, v82
	v_mov_b32_e32 v31, v82
	v_mov_b32_e32 v32, v82
	v_mov_b32_e32 v33, v82
	v_mov_b32_e32 v2, v82
	v_mov_b32_e32 v3, v82
	v_mov_b32_e32 v4, v82
	v_mov_b32_e32 v5, v82
	v_mov_b32_e32 v6, v82
	v_mov_b32_e32 v7, v82
	v_mov_b32_e32 v8, v82
	v_mov_b32_e32 v9, v82
	v_mov_b32_e32 v10, v82
	v_mov_b32_e32 v11, v82
	v_mov_b32_e32 v12, v82
	v_mov_b32_e32 v13, v82
	v_mov_b32_e32 v14, v82
	v_mov_b32_e32 v15, v82
	v_mov_b32_e32 v16, v82
	v_mov_b32_e32 v17, v82
	v_mov_b32_e32 v116, v82
	v_mov_b32_e32 v117, v82
	v_mov_b32_e32 v118, v82
	v_mov_b32_e32 v119, v82
	v_mov_b32_e32 v120, v82
	v_mov_b32_e32 v121, v82
	v_mov_b32_e32 v122, v82
	v_mov_b32_e32 v123, v82
	v_mov_b32_e32 v124, v82
	v_mov_b32_e32 v125, v82
	v_mov_b32_e32 v126, v82
	v_mov_b32_e32 v127, v82
	v_mov_b32_e32 v128, v82
	v_mov_b32_e32 v129, v82
	v_mov_b32_e32 v98, v82
	v_mov_b32_e32 v99, v82
	v_mov_b32_e32 v100, v82
	v_mov_b32_e32 v101, v82
	v_mov_b32_e32 v102, v82
	v_mov_b32_e32 v103, v82
	v_mov_b32_e32 v104, v82
	v_mov_b32_e32 v105, v82
	v_mov_b32_e32 v106, v82
	v_mov_b32_e32 v107, v82
	v_mov_b32_e32 v108, v82
	v_mov_b32_e32 v109, v82
	v_mov_b32_e32 v110, v82
	v_mov_b32_e32 v111, v82
	v_mov_b32_e32 v112, v82
	v_mov_b32_e32 v113, v82
	v_mov_b32_e32 v50, v82
	v_mov_b32_e32 v51, v82
	v_mov_b32_e32 v52, v82
	v_mov_b32_e32 v53, v82
	v_mov_b32_e32 v54, v82
	v_mov_b32_e32 v55, v82
	v_mov_b32_e32 v56, v82
	v_mov_b32_e32 v57, v82
	v_mov_b32_e32 v58, v82
	v_mov_b32_e32 v59, v82
	v_mov_b32_e32 v60, v82
	v_mov_b32_e32 v61, v82
	v_mov_b32_e32 v62, v82
	v_mov_b32_e32 v63, v82
	v_mov_b32_e32 v64, v82
	v_mov_b32_e32 v65, v82
	v_mov_b32_e32 v34, v82
	v_mov_b32_e32 v35, v82
	v_mov_b32_e32 v36, v82
	v_mov_b32_e32 v37, v82
	v_mov_b32_e32 v38, v82
	v_mov_b32_e32 v39, v82
	v_mov_b32_e32 v40, v82
	v_mov_b32_e32 v41, v82
	v_mov_b32_e32 v42, v82
	v_mov_b32_e32 v43, v82
	v_mov_b32_e32 v44, v82
	v_mov_b32_e32 v45, v82
	v_mov_b32_e32 v46, v82
	v_mov_b32_e32 v47, v82
	v_mov_b32_e32 v48, v82
	v_mov_b32_e32 v49, v82
	s_waitcnt lgkmcnt(0)
	s_barrier
	s_add_u32 s18, s6, 0xd800080
	s_addc_u32 s19, s7, 0
	s_add_u32 s22, s18, 0x20000
	s_addc_u32 s23, s19, 0
	s_add_u32 s24, s18, 0x40000
	s_addc_u32 s25, s19, 0
	s_add_u32 s26, s18, 0x60000
	s_addc_u32 s27, s19, 0
	s_add_u32 s6, s8, 0x5600080
	s_addc_u32 s7, s9, 0
	s_add_u32 s8, s6, 0x20000
	s_addc_u32 s9, s7, 0
	s_add_u32 s10, s6, 0x40000
	s_addc_u32 s11, s7, 0
	s_add_u32 s12, s6, 0x60000
	s_addc_u32 s13, s7, 0
	v_lshrrev_b32_e32 v170, 3, v204
	v_lshrrev_b32_e32 v171, 4, v204
	v_xor_b32_e32 v171, v171, v204
	v_and_b32_e32 v171, 7, v171
	v_lshlrev_b32_e32 v171, 4, v171
	v_lshl_or_b32 v170, v170, 11, v171
	v_readfirstlane_b32 s28, v204
	s_and_b32 s28, s28, 0x3c0
	s_lshl_b32 s28, s28, 4
	s_mov_b32 s3, 0
	ds_read_b128 v[130:133], v190
	ds_read_b128 v[138:141], v186
	ds_read_b128 v[134:137], v190 offset:4096
	ds_read_b128 v[142:145], v186 offset:4096
	ds_read_b128 v[146:149], v186 offset:8192
	ds_read_b128 v[150:153], v186 offset:12288
	s_add_u32 m0, s28, 0x8000
	s_nop 0
	global_load_lds_dwordx4 v170, s[6:7]
	s_add_u32 m0, s28, 0x18000
	s_nop 0
	global_load_lds_dwordx4 v170, s[18:19]
	s_add_u32 m0, s28, 0xa000
	s_nop 0
	global_load_lds_dwordx4 v170, s[8:9]
	s_add_u32 m0, s28, 0x1a000
	s_nop 0
	global_load_lds_dwordx4 v170, s[22:23]
	s_add_u32 m0, s28, 0xc000
	s_nop 0
	global_load_lds_dwordx4 v170, s[10:11]
	s_add_u32 m0, s28, 0x1c000
	s_nop 0
	global_load_lds_dwordx4 v170, s[24:25]
	s_add_u32 m0, s28, 0xe000
	s_nop 0
	global_load_lds_dwordx4 v170, s[12:13]
	s_add_u32 m0, s28, 0x1e000
	s_nop 0
	global_load_lds_dwordx4 v170, s[26:27]
	s_branch .Lg_cout_mid
.Lg_cout_top:
	ds_read_b128 v[130:133], v190
	ds_read_b128 v[138:141], v186
	ds_read_b128 v[134:137], v190 offset:4096
	ds_read_b128 v[142:145], v186 offset:4096
	ds_read_b128 v[146:149], v186 offset:8192
	ds_read_b128 v[150:153], v186 offset:12288
	s_add_u32 m0, s28, 0x8000
	v_mfma_f32_32x32x16_bf16 v[82:97], v[154:157], v[162:165], v[82:97]
	global_load_lds_dwordx4 v170, s[6:7]
	s_add_u32 m0, s28, 0x18000
	v_mfma_f32_32x32x16_bf16 v[114:129], v[158:161], v[162:165], v[114:129]
	global_load_lds_dwordx4 v170, s[18:19]
	s_add_u32 m0, s28, 0xa000
	v_mfma_f32_32x32x16_bf16 v[66:81], v[154:157], v[166:169], v[66:81]
	global_load_lds_dwordx4 v170, s[8:9]
	s_add_u32 m0, s28, 0x1a000
	v_mfma_f32_32x32x16_bf16 v[98:113], v[158:161], v[166:169], v[98:113]
	global_load_lds_dwordx4 v170, s[22:23]
	s_add_u32 m0, s28, 0xc000
	v_mfma_f32_32x32x16_bf16 v[18:33], v[154:157], v[200:203], v[18:33]
	global_load_lds_dwordx4 v170, s[10:11]
	s_add_u32 m0, s28, 0x1c000
	v_mfma_f32_32x32x16_bf16 v[50:65], v[158:161], v[200:203], v[50:65]
	global_load_lds_dwordx4 v170, s[24:25]
	s_add_u32 m0, s28, 0xe000
	v_mfma_f32_32x32x16_bf16 v[2:17], v[154:157], v[216:219], v[2:17]
	global_load_lds_dwordx4 v170, s[12:13]
	s_add_u32 m0, s28, 0x1e000
	v_mfma_f32_32x32x16_bf16 v[34:49], v[158:161], v[216:219], v[34:49]
	global_load_lds_dwordx4 v170, s[26:27]
.Lg_cout_mid:
	ds_read_b128 v[154:157], v191
	ds_read_b128 v[162:165], v187
	ds_read_b128 v[158:161], v191 offset:4096
	ds_read_b128 v[166:169], v187 offset:4096
	ds_read_b128 v[200:203], v187 offset:8192
	ds_read_b128 v[216:219], v187 offset:12288
	s_waitcnt lgkmcnt(6)
	v_mfma_f32_32x32x16_bf16 v[82:97], v[130:133], v[138:141], v[82:97]
	s_add_u32 s6, s6, 0x80
	s_addc_u32 s7, s7, 0
	v_mfma_f32_32x32x16_bf16 v[114:129], v[134:137], v[138:141], v[114:129]
	s_add_u32 s8, s8, 0x80
	s_addc_u32 s9, s9, 0
	v_mfma_f32_32x32x16_bf16 v[66:81], v[130:133], v[142:145], v[66:81]
	s_add_u32 s10, s10, 0x80
	s_addc_u32 s11, s11, 0
	v_mfma_f32_32x32x16_bf16 v[98:113], v[134:137], v[142:145], v[98:113]
	s_add_u32 s12, s12, 0x80
	s_addc_u32 s13, s13, 0
	v_mfma_f32_32x32x16_bf16 v[18:33], v[130:133], v[146:149], v[18:33]
	s_add_u32 s18, s18, 0x80
	s_addc_u32 s19, s19, 0
	v_mfma_f32_32x32x16_bf16 v[50:65], v[134:137], v[146:149], v[50:65]
	s_add_u32 s22, s22, 0x80
	s_addc_u32 s23, s23, 0
	v_mfma_f32_32x32x16_bf16 v[2:17], v[130:133], v[150:153], v[2:17]
	s_add_u32 s24, s24, 0x80
	s_addc_u32 s25, s25, 0
	v_mfma_f32_32x32x16_bf16 v[34:49], v[134:137], v[150:153], v[34:49]
	s_add_u32 s26, s26, 0x80
	s_addc_u32 s27, s27, 0
	ds_read_b128 v[130:133], v192
	ds_read_b128 v[138:141], v188
	ds_read_b128 v[134:137], v192 offset:4096
	ds_read_b128 v[142:145], v188 offset:4096
	ds_read_b128 v[146:149], v188 offset:8192
	ds_read_b128 v[150:153], v188 offset:12288
	s_waitcnt lgkmcnt(6)
	v_mfma_f32_32x32x16_bf16 v[82:97], v[154:157], v[162:165], v[82:97]
	v_mfma_f32_32x32x16_bf16 v[114:129], v[158:161], v[162:165], v[114:129]
	v_mfma_f32_32x32x16_bf16 v[66:81], v[154:157], v[166:169], v[66:81]
	v_mfma_f32_32x32x16_bf16 v[98:113], v[158:161], v[166:169], v[98:113]
	v_mfma_f32_32x32x16_bf16 v[18:33], v[154:157], v[200:203], v[18:33]
	v_mfma_f32_32x32x16_bf16 v[50:65], v[158:161], v[200:203], v[50:65]
	v_mfma_f32_32x32x16_bf16 v[2:17], v[154:157], v[216:219], v[2:17]
	v_mfma_f32_32x32x16_bf16 v[34:49], v[158:161], v[216:219], v[34:49]
	ds_read_b128 v[154:157], v193
	ds_read_b128 v[162:165], v189
	ds_read_b128 v[158:161], v193 offset:4096
	ds_read_b128 v[166:169], v189 offset:4096
	ds_read_b128 v[200:203], v189 offset:8192
	ds_read_b128 v[216:219], v189 offset:12288
	s_waitcnt lgkmcnt(6)
	v_mfma_f32_32x32x16_bf16 v[82:97], v[130:133], v[138:141], v[82:97]
	v_mfma_f32_32x32x16_bf16 v[114:129], v[134:137], v[138:141], v[114:129]
	v_mfma_f32_32x32x16_bf16 v[66:81], v[130:133], v[142:145], v[66:81]
	v_mfma_f32_32x32x16_bf16 v[98:113], v[134:137], v[142:145], v[98:113]
	v_mfma_f32_32x32x16_bf16 v[18:33], v[130:133], v[146:149], v[18:33]
	v_mfma_f32_32x32x16_bf16 v[50:65], v[134:137], v[146:149], v[50:65]
	v_mfma_f32_32x32x16_bf16 v[2:17], v[130:133], v[150:153], v[2:17]
	v_mfma_f32_32x32x16_bf16 v[34:49], v[134:137], v[150:153], v[34:49]
	s_waitcnt vmcnt(0) lgkmcnt(0)
	s_barrier
	ds_read_b128 v[130:133], v190 offset:32768
	ds_read_b128 v[138:141], v194
	ds_read_b128 v[134:137], v190 offset:36864
	ds_read_b128 v[142:145], v194 offset:4096
	ds_read_b128 v[146:149], v194 offset:8192
	ds_read_b128 v[150:153], v194 offset:12288
	s_cmp_ge_u32 s3, 14
	s_cbranch_scc1 .Lg_cout_nodma
	s_add_u32 m0, s28, 0x0
	v_mfma_f32_32x32x16_bf16 v[82:97], v[154:157], v[162:165], v[82:97]
	global_load_lds_dwordx4 v170, s[6:7]
	s_add_u32 m0, s28, 0x10000
	v_mfma_f32_32x32x16_bf16 v[114:129], v[158:161], v[162:165], v[114:129]
	global_load_lds_dwordx4 v170, s[18:19]
	s_add_u32 m0, s28, 0x2000
	v_mfma_f32_32x32x16_bf16 v[66:81], v[154:157], v[166:169], v[66:81]
	global_load_lds_dwordx4 v170, s[8:9]
	s_add_u32 m0, s28, 0x12000
	v_mfma_f32_32x32x16_bf16 v[98:113], v[158:161], v[166:169], v[98:113]
	global_load_lds_dwordx4 v170, s[22:23]
	s_add_u32 m0, s28, 0x4000
	v_mfma_f32_32x32x16_bf16 v[18:33], v[154:157], v[200:203], v[18:33]
	global_load_lds_dwordx4 v170, s[10:11]
	s_add_u32 m0, s28, 0x14000
	v_mfma_f32_32x32x16_bf16 v[50:65], v[158:161], v[200:203], v[50:65]
	global_load_lds_dwordx4 v170, s[24:25]
	s_add_u32 m0, s28, 0x6000
	v_mfma_f32_32x32x16_bf16 v[2:17], v[154:157], v[216:219], v[2:17]
	global_load_lds_dwordx4 v170, s[12:13]
	s_add_u32 m0, s28, 0x16000
	v_mfma_f32_32x32x16_bf16 v[34:49], v[158:161], v[216:219], v[34:49]
	global_load_lds_dwordx4 v170, s[26:27]
	s_branch .Lg_cout_join
.Lg_cout_nodma:
	v_mfma_f32_32x32x16_bf16 v[82:97], v[154:157], v[162:165], v[82:97]
	v_mfma_f32_32x32x16_bf16 v[114:129], v[158:161], v[162:165], v[114:129]
	v_mfma_f32_32x32x16_bf16 v[66:81], v[154:157], v[166:169], v[66:81]
	v_mfma_f32_32x32x16_bf16 v[98:113], v[158:161], v[166:169], v[98:113]
	v_mfma_f32_32x32x16_bf16 v[18:33], v[154:157], v[200:203], v[18:33]
	v_mfma_f32_32x32x16_bf16 v[50:65], v[158:161], v[200:203], v[50:65]
	v_mfma_f32_32x32x16_bf16 v[2:17], v[154:157], v[216:219], v[2:17]
	v_mfma_f32_32x32x16_bf16 v[34:49], v[158:161], v[216:219], v[34:49]
.Lg_cout_join:
	ds_read_b128 v[154:157], v191 offset:32768
	ds_read_b128 v[162:165], v195
	ds_read_b128 v[158:161], v191 offset:36864
	ds_read_b128 v[166:169], v195 offset:4096
	ds_read_b128 v[200:203], v195 offset:8192
	ds_read_b128 v[216:219], v195 offset:12288
	s_waitcnt lgkmcnt(6)
	v_mfma_f32_32x32x16_bf16 v[82:97], v[130:133], v[138:141], v[82:97]
	s_add_u32 s6, s6, 0x80
	s_addc_u32 s7, s7, 0
	v_mfma_f32_32x32x16_bf16 v[114:129], v[134:137], v[138:141], v[114:129]
	s_add_u32 s8, s8, 0x80
	s_addc_u32 s9, s9, 0
	v_mfma_f32_32x32x16_bf16 v[66:81], v[130:133], v[142:145], v[66:81]
	s_add_u32 s10, s10, 0x80
	s_addc_u32 s11, s11, 0
	v_mfma_f32_32x32x16_bf16 v[98:113], v[134:137], v[142:145], v[98:113]
	s_add_u32 s12, s12, 0x80
	s_addc_u32 s13, s13, 0
	v_mfma_f32_32x32x16_bf16 v[18:33], v[130:133], v[146:149], v[18:33]
	s_add_u32 s18, s18, 0x80
	s_addc_u32 s19, s19, 0
	v_mfma_f32_32x32x16_bf16 v[50:65], v[134:137], v[146:149], v[50:65]
	s_add_u32 s22, s22, 0x80
	s_addc_u32 s23, s23, 0
	v_mfma_f32_32x32x16_bf16 v[2:17], v[130:133], v[150:153], v[2:17]
	s_add_u32 s24, s24, 0x80
	s_addc_u32 s25, s25, 0
	v_mfma_f32_32x32x16_bf16 v[34:49], v[134:137], v[150:153], v[34:49]
	s_add_u32 s26, s26, 0x80
	s_addc_u32 s27, s27, 0
	ds_read_b128 v[130:133], v192 offset:32768
	ds_read_b128 v[138:141], v196
	ds_read_b128 v[134:137], v192 offset:36864
	ds_read_b128 v[142:145], v196 offset:4096
	ds_read_b128 v[146:149], v196 offset:8192
	ds_read_b128 v[150:153], v196 offset:12288
	s_waitcnt lgkmcnt(6)
	v_mfma_f32_32x32x16_bf16 v[82:97], v[154:157], v[162:165], v[82:97]
	v_mfma_f32_32x32x16_bf16 v[114:129], v[158:161], v[162:165], v[114:129]
	v_mfma_f32_32x32x16_bf16 v[66:81], v[154:157], v[166:169], v[66:81]
	v_mfma_f32_32x32x16_bf16 v[98:113], v[158:161], v[166:169], v[98:113]
	v_mfma_f32_32x32x16_bf16 v[18:33], v[154:157], v[200:203], v[18:33]
	v_mfma_f32_32x32x16_bf16 v[50:65], v[158:161], v[200:203], v[50:65]
	v_mfma_f32_32x32x16_bf16 v[2:17], v[154:157], v[216:219], v[2:17]
	v_mfma_f32_32x32x16_bf16 v[34:49], v[158:161], v[216:219], v[34:49]
	ds_read_b128 v[154:157], v193 offset:32768
	ds_read_b128 v[162:165], v197
	ds_read_b128 v[158:161], v193 offset:36864
	ds_read_b128 v[166:169], v197 offset:4096
	ds_read_b128 v[200:203], v197 offset:8192
	ds_read_b128 v[216:219], v197 offset:12288
	s_waitcnt lgkmcnt(6)
	v_mfma_f32_32x32x16_bf16 v[82:97], v[130:133], v[138:141], v[82:97]
	v_mfma_f32_32x32x16_bf16 v[114:129], v[134:137], v[138:141], v[114:129]
	v_mfma_f32_32x32x16_bf16 v[66:81], v[130:133], v[142:145], v[66:81]
	v_mfma_f32_32x32x16_bf16 v[98:113], v[134:137], v[142:145], v[98:113]
	v_mfma_f32_32x32x16_bf16 v[18:33], v[130:133], v[146:149], v[18:33]
	v_mfma_f32_32x32x16_bf16 v[50:65], v[134:137], v[146:149], v[50:65]
	v_mfma_f32_32x32x16_bf16 v[2:17], v[130:133], v[150:153], v[2:17]
	v_mfma_f32_32x32x16_bf16 v[34:49], v[134:137], v[150:153], v[34:49]
	s_waitcnt vmcnt(0) lgkmcnt(0)
	s_barrier
	s_add_i32 s3, s3, 2
	s_cmp_lt_u32 s3, 16
	s_cbranch_scc1 .Lg_cout_top
	v_mfma_f32_32x32x16_bf16 v[82:97], v[154:157], v[162:165], v[82:97]
	v_mfma_f32_32x32x16_bf16 v[114:129], v[158:161], v[162:165], v[114:129]
	v_mfma_f32_32x32x16_bf16 v[66:81], v[154:157], v[166:169], v[66:81]
	v_mfma_f32_32x32x16_bf16 v[98:113], v[158:161], v[166:169], v[98:113]
	v_mfma_f32_32x32x16_bf16 v[18:33], v[154:157], v[200:203], v[18:33]
	v_mfma_f32_32x32x16_bf16 v[50:65], v[158:161], v[200:203], v[50:65]
	v_mfma_f32_32x32x16_bf16 v[2:17], v[154:157], v[216:219], v[2:17]
	v_mfma_f32_32x32x16_bf16 v[34:49], v[158:161], v[216:219], v[34:49]
	s_nop 7
	s_nop 7
	s_branch .LBB0_1141

.LBB0_1243:
	s_or_b64 exec, exec, s[10:11]
	v_readlane_b32 s12, v250, 9
	v_readlane_b32 s14, v250, 11
	v_readlane_b32 s15, v250, 12
	s_add_u32 s8, s14, s8
	s_addc_u32 s9, s15, s9
	s_add_u32 s10, s18, s0
	v_mov_b32_e32 v98, 0
	s_addc_u32 s11, s19, s1
	s_mov_b32 s3, 0
	v_mov_b32_e32 v99, v98
	v_mov_b32_e32 v100, v98
	v_mov_b32_e32 v101, v98
	v_mov_b32_e32 v102, v98
	v_mov_b32_e32 v103, v98
	v_mov_b32_e32 v104, v98
	v_mov_b32_e32 v105, v98
	v_mov_b32_e32 v106, v98
	v_mov_b32_e32 v107, v98
	v_mov_b32_e32 v108, v98
	v_mov_b32_e32 v109, v98
	v_mov_b32_e32 v110, v98
	v_mov_b32_e32 v111, v98
	v_mov_b32_e32 v112, v98
	v_mov_b32_e32 v113, v98
	v_mov_b32_e32 v82, v98
	v_mov_b32_e32 v83, v98
	v_mov_b32_e32 v84, v98
	v_mov_b32_e32 v85, v98
	v_mov_b32_e32 v86, v98
	v_mov_b32_e32 v87, v98
	v_mov_b32_e32 v88, v98
	v_mov_b32_e32 v89, v98
	v_mov_b32_e32 v90, v98
	v_mov_b32_e32 v91, v98
	v_mov_b32_e32 v92, v98
	v_mov_b32_e32 v93, v98
	v_mov_b32_e32 v94, v98
	v_mov_b32_e32 v95, v98
	v_mov_b32_e32 v96, v98
	v_mov_b32_e32 v97, v98
	v_mov_b32_e32 v34, v98
	v_mov_b32_e32 v35, v98
	v_mov_b32_e32 v36, v98
	v_mov_b32_e32 v37, v98
	v_mov_b32_e32 v38, v98
	v_mov_b32_e32 v39, v98
	v_mov_b32_e32 v40, v98
	v_mov_b32_e32 v41, v98
	v_mov_b32_e32 v42, v98
	v_mov_b32_e32 v43, v98
	v_mov_b32_e32 v44, v98
	v_mov_b32_e32 v45, v98
	v_mov_b32_e32 v46, v98
	v_mov_b32_e32 v47, v98
	v_mov_b32_e32 v48, v98
	v_mov_b32_e32 v49, v98
	v_mov_b32_e32 v18, v98
	v_mov_b32_e32 v19, v98
	v_mov_b32_e32 v20, v98
	v_mov_b32_e32 v21, v98
	v_mov_b32_e32 v22, v98
	v_mov_b32_e32 v23, v98
	v_mov_b32_e32 v24, v98
	v_mov_b32_e32 v25, v98
	v_mov_b32_e32 v26, v98
	v_mov_b32_e32 v27, v98
	v_mov_b32_e32 v28, v98
	v_mov_b32_e32 v29, v98
	v_mov_b32_e32 v30, v98
	v_mov_b32_e32 v31, v98
	v_mov_b32_e32 v32, v98
	v_mov_b32_e32 v33, v98
	v_mov_b32_e32 v114, v98
	v_mov_b32_e32 v115, v98
	v_mov_b32_e32 v116, v98
	v_mov_b32_e32 v117, v98
	v_mov_b32_e32 v118, v98
	v_mov_b32_e32 v119, v98
	v_mov_b32_e32 v120, v98
	v_mov_b32_e32 v121, v98
	v_mov_b32_e32 v122, v98
	v_mov_b32_e32 v123, v98
	v_mov_b32_e32 v124, v98
	v_mov_b32_e32 v125, v98
	v_mov_b32_e32 v126, v98
	v_mov_b32_e32 v127, v98
	v_mov_b32_e32 v128, v98
	v_mov_b32_e32 v129, v98
	v_mov_b32_e32 v66, v98
	v_mov_b32_e32 v67, v98
	v_mov_b32_e32 v68, v98
	v_mov_b32_e32 v69, v98
	v_mov_b32_e32 v70, v98
	v_mov_b32_e32 v71, v98
	v_mov_b32_e32 v72, v98
	v_mov_b32_e32 v73, v98
	v_mov_b32_e32 v74, v98
	v_mov_b32_e32 v75, v98
	v_mov_b32_e32 v76, v98
	v_mov_b32_e32 v77, v98
	v_mov_b32_e32 v78, v98
	v_mov_b32_e32 v79, v98
	v_mov_b32_e32 v80, v98
	v_mov_b32_e32 v81, v98
	v_mov_b32_e32 v50, v98
	v_mov_b32_e32 v51, v98
	v_mov_b32_e32 v52, v98
	v_mov_b32_e32 v53, v98
	v_mov_b32_e32 v54, v98
	v_mov_b32_e32 v55, v98
	v_mov_b32_e32 v56, v98
	v_mov_b32_e32 v57, v98
	v_mov_b32_e32 v58, v98
	v_mov_b32_e32 v59, v98
	v_mov_b32_e32 v60, v98
	v_mov_b32_e32 v61, v98
	v_mov_b32_e32 v62, v98
	v_mov_b32_e32 v63, v98
	v_mov_b32_e32 v64, v98
	v_mov_b32_e32 v65, v98
	v_mov_b32_e32 v2, v98
	v_mov_b32_e32 v3, v98
	v_mov_b32_e32 v4, v98
	v_mov_b32_e32 v5, v98
	v_mov_b32_e32 v6, v98
	v_mov_b32_e32 v7, v98
	v_mov_b32_e32 v8, v98
	v_mov_b32_e32 v9, v98
	v_mov_b32_e32 v10, v98
	v_mov_b32_e32 v11, v98
	v_mov_b32_e32 v12, v98
	v_mov_b32_e32 v13, v98
	v_mov_b32_e32 v14, v98
	v_mov_b32_e32 v15, v98
	v_mov_b32_e32 v16, v98
	v_mov_b32_e32 v17, v98
	v_readlane_b32 s13, v250, 10
	s_add_u32 s22, s8, 0x5800080
	s_addc_u32 s23, s9, 0
	s_add_u32 s24, s22, 0x20000
	s_addc_u32 s25, s23, 0
	s_add_u32 s26, s22, 0x40000
	s_addc_u32 s27, s23, 0
	s_add_u32 s28, s22, 0x60000
	s_addc_u32 s29, s23, 0
	s_add_u32 s8, s10, 0x4000080
	s_addc_u32 s9, s11, 0
	s_add_u32 s10, s8, 0x20000
	s_addc_u32 s11, s9, 0
	s_add_u32 s12, s8, 0x40000
	s_addc_u32 s13, s9, 0
	s_add_u32 s14, s8, 0x60000
	s_addc_u32 s15, s9, 0
	v_lshrrev_b32_e32 v170, 3, v204
	v_lshrrev_b32_e32 v171, 4, v204
	v_xor_b32_e32 v171, v171, v204
	v_and_b32_e32 v171, 7, v171
	v_lshlrev_b32_e32 v171, 4, v171
	v_lshl_or_b32 v170, v170, 11, v171
	v_readfirstlane_b32 s30, v204
	s_and_b32 s30, s30, 0x3c0
	s_lshl_b32 s30, s30, 4
	s_mov_b32 s3, 0
	ds_read_b128 v[130:133], v220
	ds_read_b128 v[138:141], v203
	ds_read_b128 v[134:137], v220 offset:4096
	ds_read_b128 v[142:145], v203 offset:4096
	ds_read_b128 v[146:149], v203 offset:8192
	ds_read_b128 v[150:153], v203 offset:12288
	s_add_u32 m0, s30, 0x8000
	s_nop 0
	global_load_lds_dwordx4 v170, s[8:9]
	s_add_u32 m0, s30, 0x18000
	s_nop 0
	global_load_lds_dwordx4 v170, s[22:23]
	s_add_u32 m0, s30, 0xa000
	s_nop 0
	global_load_lds_dwordx4 v170, s[10:11]
	s_add_u32 m0, s30, 0x1a000
	s_nop 0
	global_load_lds_dwordx4 v170, s[24:25]
	s_add_u32 m0, s30, 0xc000
	s_nop 0
	global_load_lds_dwordx4 v170, s[12:13]
	s_add_u32 m0, s30, 0x1c000
	s_nop 0
	global_load_lds_dwordx4 v170, s[26:27]
	s_add_u32 m0, s30, 0xe000
	s_nop 0
	global_load_lds_dwordx4 v170, s[14:15]
	s_add_u32 m0, s30, 0x1e000
	s_nop 0
	global_load_lds_dwordx4 v170, s[28:29]
	s_branch .Lg_aqkv_mid
.Lg_aqkv_top:
	ds_read_b128 v[130:133], v220
	ds_read_b128 v[138:141], v203
	ds_read_b128 v[134:137], v220 offset:4096
	ds_read_b128 v[142:145], v203 offset:4096
	ds_read_b128 v[146:149], v203 offset:8192
	ds_read_b128 v[150:153], v203 offset:12288
	s_add_u32 m0, s30, 0x8000
	v_mfma_f32_32x32x16_bf16 v[98:113], v[154:157], v[162:165], v[98:113]
	global_load_lds_dwordx4 v170, s[8:9]
	s_add_u32 m0, s30, 0x18000
	v_mfma_f32_32x32x16_bf16 v[114:129], v[158:161], v[162:165], v[114:129]
	global_load_lds_dwordx4 v170, s[22:23]
	s_add_u32 m0, s30, 0xa000
	v_mfma_f32_32x32x16_bf16 v[82:97], v[154:157], v[166:169], v[82:97]
	global_load_lds_dwordx4 v170, s[10:11]
	s_add_u32 m0, s30, 0x1a000
	v_mfma_f32_32x32x16_bf16 v[66:81], v[158:161], v[166:169], v[66:81]
	global_load_lds_dwordx4 v170, s[24:25]
	s_add_u32 m0, s30, 0xc000
	v_mfma_f32_32x32x16_bf16 v[34:49], v[154:157], v[176:179], v[34:49]
	global_load_lds_dwordx4 v170, s[12:13]
	s_add_u32 m0, s30, 0x1c000
	v_mfma_f32_32x32x16_bf16 v[50:65], v[158:161], v[176:179], v[50:65]
	global_load_lds_dwordx4 v170, s[26:27]
	s_add_u32 m0, s30, 0xe000
	v_mfma_f32_32x32x16_bf16 v[18:33], v[154:157], v[180:183], v[18:33]
	global_load_lds_dwordx4 v170, s[14:15]
	s_add_u32 m0, s30, 0x1e000
	v_mfma_f32_32x32x16_bf16 v[2:17], v[158:161], v[180:183], v[2:17]
	global_load_lds_dwordx4 v170, s[28:29]
.Lg_aqkv_mid:
	ds_read_b128 v[154:157], v221
	ds_read_b128 v[162:165], v216
	ds_read_b128 v[158:161], v221 offset:4096
	ds_read_b128 v[166:169], v216 offset:4096
	ds_read_b128 v[176:179], v216 offset:8192
	ds_read_b128 v[180:183], v216 offset:12288
	s_waitcnt lgkmcnt(6)
	v_mfma_f32_32x32x16_bf16 v[98:113], v[130:133], v[138:141], v[98:113]
	s_add_u32 s8, s8, 0x80
	s_addc_u32 s9, s9, 0
	v_mfma_f32_32x32x16_bf16 v[114:129], v[134:137], v[138:141], v[114:129]
	s_add_u32 s10, s10, 0x80
	s_addc_u32 s11, s11, 0
	v_mfma_f32_32x32x16_bf16 v[82:97], v[130:133], v[142:145], v[82:97]
	s_add_u32 s12, s12, 0x80
	s_addc_u32 s13, s13, 0
	v_mfma_f32_32x32x16_bf16 v[66:81], v[134:137], v[142:145], v[66:81]
	s_add_u32 s14, s14, 0x80
	s_addc_u32 s15, s15, 0
	v_mfma_f32_32x32x16_bf16 v[34:49], v[130:133], v[146:149], v[34:49]
	s_add_u32 s22, s22, 0x80
	s_addc_u32 s23, s23, 0
	v_mfma_f32_32x32x16_bf16 v[50:65], v[134:137], v[146:149], v[50:65]
	s_add_u32 s24, s24, 0x80
	s_addc_u32 s25, s25, 0
	v_mfma_f32_32x32x16_bf16 v[18:33], v[130:133], v[150:153], v[18:33]
	s_add_u32 s26, s26, 0x80
	s_addc_u32 s27, s27, 0
	v_mfma_f32_32x32x16_bf16 v[2:17], v[134:137], v[150:153], v[2:17]
	s_add_u32 s28, s28, 0x80
	s_addc_u32 s29, s29, 0
	ds_read_b128 v[130:133], v222
	ds_read_b128 v[138:141], v217
	ds_read_b128 v[134:137], v222 offset:4096
	ds_read_b128 v[142:145], v217 offset:4096
	ds_read_b128 v[146:149], v217 offset:8192
	ds_read_b128 v[150:153], v217 offset:12288
	s_waitcnt lgkmcnt(6)
	v_mfma_f32_32x32x16_bf16 v[98:113], v[154:157], v[162:165], v[98:113]
	v_mfma_f32_32x32x16_bf16 v[114:129], v[158:161], v[162:165], v[114:129]
	v_mfma_f32_32x32x16_bf16 v[82:97], v[154:157], v[166:169], v[82:97]
	v_mfma_f32_32x32x16_bf16 v[66:81], v[158:161], v[166:169], v[66:81]
	v_mfma_f32_32x32x16_bf16 v[34:49], v[154:157], v[176:179], v[34:49]
	v_mfma_f32_32x32x16_bf16 v[50:65], v[158:161], v[176:179], v[50:65]
	v_mfma_f32_32x32x16_bf16 v[18:33], v[154:157], v[180:183], v[18:33]
	v_mfma_f32_32x32x16_bf16 v[2:17], v[158:161], v[180:183], v[2:17]
	ds_read_b128 v[154:157], v223
	ds_read_b128 v[162:165], v218
	ds_read_b128 v[158:161], v223 offset:4096
	ds_read_b128 v[166:169], v218 offset:4096
	ds_read_b128 v[176:179], v218 offset:8192
	ds_read_b128 v[180:183], v218 offset:12288
	s_waitcnt lgkmcnt(6)
	v_mfma_f32_32x32x16_bf16 v[98:113], v[130:133], v[138:141], v[98:113]
	v_mfma_f32_32x32x16_bf16 v[114:129], v[134:137], v[138:141], v[114:129]
	v_mfma_f32_32x32x16_bf16 v[82:97], v[130:133], v[142:145], v[82:97]
	v_mfma_f32_32x32x16_bf16 v[66:81], v[134:137], v[142:145], v[66:81]
	v_mfma_f32_32x32x16_bf16 v[34:49], v[130:133], v[146:149], v[34:49]
	v_mfma_f32_32x32x16_bf16 v[50:65], v[134:137], v[146:149], v[50:65]
	v_mfma_f32_32x32x16_bf16 v[18:33], v[130:133], v[150:153], v[18:33]
	v_mfma_f32_32x32x16_bf16 v[2:17], v[134:137], v[150:153], v[2:17]
	s_waitcnt vmcnt(0) lgkmcnt(0)
	s_barrier
	ds_read_b128 v[130:133], v220 offset:32768
	ds_read_b128 v[138:141], v224
	ds_read_b128 v[134:137], v220 offset:36864
	ds_read_b128 v[142:145], v224 offset:4096
	ds_read_b128 v[146:149], v224 offset:8192
	ds_read_b128 v[150:153], v224 offset:12288
	s_cmp_ge_u32 s3, 14
	s_cbranch_scc1 .Lg_aqkv_nodma
	s_add_u32 m0, s30, 0x0
	v_mfma_f32_32x32x16_bf16 v[98:113], v[154:157], v[162:165], v[98:113]
	global_load_lds_dwordx4 v170, s[8:9]
	s_add_u32 m0, s30, 0x10000
	v_mfma_f32_32x32x16_bf16 v[114:129], v[158:161], v[162:165], v[114:129]
	global_load_lds_dwordx4 v170, s[22:23]
	s_add_u32 m0, s30, 0x2000
	v_mfma_f32_32x32x16_bf16 v[82:97], v[154:157], v[166:169], v[82:97]
	global_load_lds_dwordx4 v170, s[10:11]
	s_add_u32 m0, s30, 0x12000
	v_mfma_f32_32x32x16_bf16 v[66:81], v[158:161], v[166:169], v[66:81]
	global_load_lds_dwordx4 v170, s[24:25]
	s_add_u32 m0, s30, 0x4000
	v_mfma_f32_32x32x16_bf16 v[34:49], v[154:157], v[176:179], v[34:49]
	global_load_lds_dwordx4 v170, s[12:13]
	s_add_u32 m0, s30, 0x14000
	v_mfma_f32_32x32x16_bf16 v[50:65], v[158:161], v[176:179], v[50:65]
	global_load_lds_dwordx4 v170, s[26:27]
	s_add_u32 m0, s30, 0x6000
	v_mfma_f32_32x32x16_bf16 v[18:33], v[154:157], v[180:183], v[18:33]
	global_load_lds_dwordx4 v170, s[14:15]
	s_add_u32 m0, s30, 0x16000
	v_mfma_f32_32x32x16_bf16 v[2:17], v[158:161], v[180:183], v[2:17]
	global_load_lds_dwordx4 v170, s[28:29]
	s_branch .Lg_aqkv_join
.Lg_aqkv_nodma:
	v_mfma_f32_32x32x16_bf16 v[98:113], v[154:157], v[162:165], v[98:113]
	v_mfma_f32_32x32x16_bf16 v[114:129], v[158:161], v[162:165], v[114:129]
	v_mfma_f32_32x32x16_bf16 v[82:97], v[154:157], v[166:169], v[82:97]
	v_mfma_f32_32x32x16_bf16 v[66:81], v[158:161], v[166:169], v[66:81]
	v_mfma_f32_32x32x16_bf16 v[34:49], v[154:157], v[176:179], v[34:49]
	v_mfma_f32_32x32x16_bf16 v[50:65], v[158:161], v[176:179], v[50:65]
	v_mfma_f32_32x32x16_bf16 v[18:33], v[154:157], v[180:183], v[18:33]
	v_mfma_f32_32x32x16_bf16 v[2:17], v[158:161], v[180:183], v[2:17]
.Lg_aqkv_join:
	ds_read_b128 v[154:157], v221 offset:32768
	ds_read_b128 v[162:165], v225
	ds_read_b128 v[158:161], v221 offset:36864
	ds_read_b128 v[166:169], v225 offset:4096
	ds_read_b128 v[176:179], v225 offset:8192
	ds_read_b128 v[180:183], v225 offset:12288
	s_waitcnt lgkmcnt(6)
	v_mfma_f32_32x32x16_bf16 v[98:113], v[130:133], v[138:141], v[98:113]
	s_add_u32 s8, s8, 0x80
	s_addc_u32 s9, s9, 0
	v_mfma_f32_32x32x16_bf16 v[114:129], v[134:137], v[138:141], v[114:129]
	s_add_u32 s10, s10, 0x80
	s_addc_u32 s11, s11, 0
	v_mfma_f32_32x32x16_bf16 v[82:97], v[130:133], v[142:145], v[82:97]
	s_add_u32 s12, s12, 0x80
	s_addc_u32 s13, s13, 0
	v_mfma_f32_32x32x16_bf16 v[66:81], v[134:137], v[142:145], v[66:81]
	s_add_u32 s14, s14, 0x80
	s_addc_u32 s15, s15, 0
	v_mfma_f32_32x32x16_bf16 v[34:49], v[130:133], v[146:149], v[34:49]
	s_add_u32 s22, s22, 0x80
	s_addc_u32 s23, s23, 0
	v_mfma_f32_32x32x16_bf16 v[50:65], v[134:137], v[146:149], v[50:65]
	s_add_u32 s24, s24, 0x80
	s_addc_u32 s25, s25, 0
	v_mfma_f32_32x32x16_bf16 v[18:33], v[130:133], v[150:153], v[18:33]
	s_add_u32 s26, s26, 0x80
	s_addc_u32 s27, s27, 0
	v_mfma_f32_32x32x16_bf16 v[2:17], v[134:137], v[150:153], v[2:17]
	s_add_u32 s28, s28, 0x80
	s_addc_u32 s29, s29, 0
	ds_read_b128 v[130:133], v222 offset:32768
	ds_read_b128 v[138:141], v226
	ds_read_b128 v[134:137], v222 offset:36864
	ds_read_b128 v[142:145], v226 offset:4096
	ds_read_b128 v[146:149], v226 offset:8192
	ds_read_b128 v[150:153], v226 offset:12288
	s_waitcnt lgkmcnt(6)
	v_mfma_f32_32x32x16_bf16 v[98:113], v[154:157], v[162:165], v[98:113]
	v_mfma_f32_32x32x16_bf16 v[114:129], v[158:161], v[162:165], v[114:129]
	v_mfma_f32_32x32x16_bf16 v[82:97], v[154:157], v[166:169], v[82:97]
	v_mfma_f32_32x32x16_bf16 v[66:81], v[158:161], v[166:169], v[66:81]
	v_mfma_f32_32x32x16_bf16 v[34:49], v[154:157], v[176:179], v[34:49]
	v_mfma_f32_32x32x16_bf16 v[50:65], v[158:161], v[176:179], v[50:65]
	v_mfma_f32_32x32x16_bf16 v[18:33], v[154:157], v[180:183], v[18:33]
	v_mfma_f32_32x32x16_bf16 v[2:17], v[158:161], v[180:183], v[2:17]
	ds_read_b128 v[154:157], v223 offset:32768
	ds_read_b128 v[162:165], v227
	ds_read_b128 v[158:161], v223 offset:36864
	ds_read_b128 v[166:169], v227 offset:4096
	ds_read_b128 v[176:179], v227 offset:8192
	ds_read_b128 v[180:183], v227 offset:12288
	s_waitcnt lgkmcnt(6)
	v_mfma_f32_32x32x16_bf16 v[98:113], v[130:133], v[138:141], v[98:113]
	v_mfma_f32_32x32x16_bf16 v[114:129], v[134:137], v[138:141], v[114:129]
	v_mfma_f32_32x32x16_bf16 v[82:97], v[130:133], v[142:145], v[82:97]
	v_mfma_f32_32x32x16_bf16 v[66:81], v[134:137], v[142:145], v[66:81]
	v_mfma_f32_32x32x16_bf16 v[34:49], v[130:133], v[146:149], v[34:49]
	v_mfma_f32_32x32x16_bf16 v[50:65], v[134:137], v[146:149], v[50:65]
	v_mfma_f32_32x32x16_bf16 v[18:33], v[130:133], v[150:153], v[18:33]
	v_mfma_f32_32x32x16_bf16 v[2:17], v[134:137], v[150:153], v[2:17]
	s_waitcnt vmcnt(0) lgkmcnt(0)
	s_barrier
	s_add_i32 s3, s3, 2
	s_cmp_lt_u32 s3, 16
	s_cbranch_scc1 .Lg_aqkv_top
	v_mfma_f32_32x32x16_bf16 v[98:113], v[154:157], v[162:165], v[98:113]
	v_mfma_f32_32x32x16_bf16 v[114:129], v[158:161], v[162:165], v[114:129]
	v_mfma_f32_32x32x16_bf16 v[82:97], v[154:157], v[166:169], v[82:97]
	v_mfma_f32_32x32x16_bf16 v[66:81], v[158:161], v[166:169], v[66:81]
	v_mfma_f32_32x32x16_bf16 v[34:49], v[154:157], v[176:179], v[34:49]
	v_mfma_f32_32x32x16_bf16 v[50:65], v[158:161], v[176:179], v[50:65]
	v_mfma_f32_32x32x16_bf16 v[18:33], v[154:157], v[180:183], v[18:33]
	v_mfma_f32_32x32x16_bf16 v[2:17], v[158:161], v[180:183], v[2:17]
	s_nop 7
	s_nop 7
	s_branch .LBB0_1261

.LBB0_1508:
	s_bfe_u32 s4, s18, 0x20003
	s_lshr_b32 s0, s18, 5
	s_lshl_b32 s0, s0, 3
	s_and_b32 s1, s18, 7
	s_add_i32 s0, s0, s1
	s_lshl_b32 s2, s0, 8
	s_ashr_i32 s3, s2, 31
	s_ashr_i32 s5, s4, 31
	s_lshl_b64 s[0:1], s[4:5], 19
	s_lshl_b64 s[6:7], s[2:3], 11
	v_readlane_b32 s8, v252, 31
	v_readlane_b32 s9, v252, 32
	s_add_u32 s8, s8, s6
	v_mov_b32_e32 v34, v174
	s_addc_u32 s9, s9, s7
	s_add_u32 s10, s14, s0
	v_lshlrev_b32_e32 v0, 4, v34
	v_ashrrev_i32_e32 v35, 3, v34
	v_and_b32_e32 v0, 0x70, v0
	s_addc_u32 s11, s15, s1
	v_lshl_or_b32 v0, v35, 11, v0
	v_lshl_add_u64 v[26:27], s[10:11], 0, v[0:1]
	v_add_co_u32_e32 v10, vcc, s52, v26
	v_lshl_add_u64 v[28:29], s[8:9], 0, v[0:1]
	s_nop 0
	v_addc_co_u32_e32 v11, vcc, 0, v27, vcc
	v_add_co_u32_e32 v14, vcc, s52, v28
	global_load_dwordx4 v[2:5], v0, s[10:11]
	global_load_dwordx4 v[6:9], v0, s[8:9]
	v_addc_co_u32_e32 v15, vcc, 0, v29, vcc
	v_add_co_u32_e32 v18, vcc, s56, v26
	global_load_dwordx4 v[10:13], v[10:11], off
	s_nop 0
	global_load_dwordx4 v[14:17], v[14:15], off
	v_addc_co_u32_e32 v19, vcc, 0, v27, vcc
	v_add_co_u32_e32 v22, vcc, s56, v28
	v_readlane_b32 s8, v250, 9
	s_nop 0
	v_addc_co_u32_e32 v23, vcc, 0, v29, vcc
	v_add_co_u32_e32 v26, vcc, s57, v26
	global_load_dwordx4 v[18:21], v[18:19], off
	s_nop 0
	global_load_dwordx4 v[22:25], v[22:23], off
	v_addc_co_u32_e32 v27, vcc, 0, v27, vcc
	v_add_co_u32_e32 v30, vcc, s57, v28
	v_lshrrev_b32_e32 v36, 1, v35
	s_nop 0
	v_addc_co_u32_e32 v31, vcc, 0, v29, vcc
	global_load_dwordx4 v[26:29], v[26:27], off
	s_nop 0
	global_load_dwordx4 v[30:33], v[30:31], off
	v_readlane_b32 s10, v250, 11
	v_xor_b32_e32 v34, v36, v34
	v_readlane_b32 s11, v250, 12
	s_add_u32 s6, s10, s6
	v_lshlrev_b32_e32 v35, 7, v35
	v_lshlrev_b32_e32 v34, 4, v34
	s_addc_u32 s7, s11, s7
	v_mov_b32_e32 v82, 0
	v_and_or_b32 v198, v34, s55, v35
	v_readlane_b32 s9, v250, 10
	s_add_u32 s8, s16, s0
	s_mov_b32 s3, 0
	v_mov_b32_e32 v83, v82
	v_mov_b32_e32 v84, v82
	v_mov_b32_e32 v85, v82
	v_mov_b32_e32 v86, v82
	v_mov_b32_e32 v87, v82
	v_mov_b32_e32 v88, v82
	v_mov_b32_e32 v89, v82
	v_mov_b32_e32 v90, v82
	v_mov_b32_e32 v91, v82
	v_mov_b32_e32 v92, v82
	v_mov_b32_e32 v93, v82
	v_mov_b32_e32 v94, v82
	v_mov_b32_e32 v95, v82
	v_mov_b32_e32 v96, v82
	v_mov_b32_e32 v97, v82
	v_mov_b32_e32 v66, v82
	v_add_u32_e32 v199, 0x10000, v198
	s_addc_u32 s9, s17, s1
	v_mov_b32_e32 v67, v82
	v_mov_b32_e32 v68, v82
	v_mov_b32_e32 v69, v82
	v_mov_b32_e32 v70, v82
	v_mov_b32_e32 v71, v82
	v_mov_b32_e32 v72, v82
	v_mov_b32_e32 v73, v82
	v_mov_b32_e32 v74, v82
	v_mov_b32_e32 v75, v82
	v_mov_b32_e32 v76, v82
	v_mov_b32_e32 v77, v82
	v_mov_b32_e32 v78, v82
	v_mov_b32_e32 v79, v82
	v_mov_b32_e32 v80, v82
	v_mov_b32_e32 v81, v82
	v_mov_b32_e32 v114, v82
	v_mov_b32_e32 v115, v82
	v_mov_b32_e32 v116, v82
	v_mov_b32_e32 v117, v82
	s_waitcnt vmcnt(7)
	ds_write_b128 v198, v[2:5]
	s_waitcnt vmcnt(6)
	ds_write_b128 v199, v[6:9]
	s_waitcnt vmcnt(5)
	ds_write_b128 v198, v[10:13] offset:8192
	s_waitcnt vmcnt(4)
	ds_write_b128 v199, v[14:17] offset:8192
	s_waitcnt vmcnt(3)
	ds_write_b128 v198, v[18:21] offset:16384
	s_waitcnt vmcnt(2)
	ds_write_b128 v199, v[22:25] offset:16384
	s_waitcnt vmcnt(1)
	ds_write_b128 v198, v[26:29] offset:24576
	s_waitcnt vmcnt(0)
	ds_write_b128 v199, v[30:33] offset:24576
	v_mov_b32_e32 v18, v82
	v_mov_b32_e32 v19, v82
	v_mov_b32_e32 v20, v82
	v_mov_b32_e32 v21, v82
	v_mov_b32_e32 v22, v82
	v_mov_b32_e32 v23, v82
	v_mov_b32_e32 v24, v82
	v_mov_b32_e32 v25, v82
	v_mov_b32_e32 v26, v82
	v_mov_b32_e32 v27, v82
	v_mov_b32_e32 v28, v82
	v_mov_b32_e32 v29, v82
	v_mov_b32_e32 v30, v82
	v_mov_b32_e32 v31, v82
	v_mov_b32_e32 v32, v82
	v_mov_b32_e32 v33, v82
	v_mov_b32_e32 v2, v82
	v_mov_b32_e32 v3, v82
	v_mov_b32_e32 v4, v82
	v_mov_b32_e32 v5, v82
	v_mov_b32_e32 v6, v82
	v_mov_b32_e32 v7, v82
	v_mov_b32_e32 v8, v82
	v_mov_b32_e32 v9, v82
	v_mov_b32_e32 v10, v82
	v_mov_b32_e32 v11, v82
	v_mov_b32_e32 v12, v82
	v_mov_b32_e32 v13, v82
	v_mov_b32_e32 v14, v82
	v_mov_b32_e32 v15, v82
	v_mov_b32_e32 v16, v82
	v_mov_b32_e32 v17, v82
	v_mov_b32_e32 v118, v82
	v_mov_b32_e32 v119, v82
	v_mov_b32_e32 v120, v82
	v_mov_b32_e32 v121, v82
	v_mov_b32_e32 v122, v82
	v_mov_b32_e32 v123, v82
	v_mov_b32_e32 v124, v82
	v_mov_b32_e32 v125, v82
	v_mov_b32_e32 v126, v82
	v_mov_b32_e32 v127, v82
	v_mov_b32_e32 v128, v82
	v_mov_b32_e32 v129, v82
	v_mov_b32_e32 v98, v82
	v_mov_b32_e32 v99, v82
	v_mov_b32_e32 v100, v82
	v_mov_b32_e32 v101, v82
	v_mov_b32_e32 v102, v82
	v_mov_b32_e32 v103, v82
	v_mov_b32_e32 v104, v82
	v_mov_b32_e32 v105, v82
	v_mov_b32_e32 v106, v82
	v_mov_b32_e32 v107, v82
	v_mov_b32_e32 v108, v82
	v_mov_b32_e32 v109, v82
	v_mov_b32_e32 v110, v82
	v_mov_b32_e32 v111, v82
	v_mov_b32_e32 v112, v82
	v_mov_b32_e32 v113, v82
	v_mov_b32_e32 v50, v82
	v_mov_b32_e32 v51, v82
	v_mov_b32_e32 v52, v82
	v_mov_b32_e32 v53, v82
	v_mov_b32_e32 v54, v82
	v_mov_b32_e32 v55, v82
	v_mov_b32_e32 v56, v82
	v_mov_b32_e32 v57, v82
	v_mov_b32_e32 v58, v82
	v_mov_b32_e32 v59, v82
	v_mov_b32_e32 v60, v82
	v_mov_b32_e32 v61, v82
	v_mov_b32_e32 v62, v82
	v_mov_b32_e32 v63, v82
	v_mov_b32_e32 v64, v82
	v_mov_b32_e32 v65, v82
	v_mov_b32_e32 v34, v82
	v_mov_b32_e32 v35, v82
	v_mov_b32_e32 v36, v82
	v_mov_b32_e32 v37, v82
	v_mov_b32_e32 v38, v82
	v_mov_b32_e32 v39, v82
	v_mov_b32_e32 v40, v82
	v_mov_b32_e32 v41, v82
	v_mov_b32_e32 v42, v82
	v_mov_b32_e32 v43, v82
	v_mov_b32_e32 v44, v82
	v_mov_b32_e32 v45, v82
	v_mov_b32_e32 v46, v82
	v_mov_b32_e32 v47, v82
	v_mov_b32_e32 v48, v82
	v_mov_b32_e32 v49, v82
	s_waitcnt lgkmcnt(0)
	s_barrier
	s_add_u32 s22, s6, 0xd800080
	s_addc_u32 s23, s7, 0
	s_add_u32 s24, s22, 0x20000
	s_addc_u32 s25, s23, 0
	s_add_u32 s26, s22, 0x40000
	s_addc_u32 s27, s23, 0
	s_add_u32 s28, s22, 0x60000
	s_addc_u32 s29, s23, 0
	s_add_u32 s6, s8, 0x4c00080
	s_addc_u32 s7, s9, 0
	s_add_u32 s8, s6, 0x20000
	s_addc_u32 s9, s7, 0
	s_add_u32 s10, s6, 0x40000
	s_addc_u32 s11, s7, 0
	s_add_u32 s12, s6, 0x60000
	s_addc_u32 s13, s7, 0
	v_lshrrev_b32_e32 v170, 3, v204
	v_lshrrev_b32_e32 v171, 4, v204
	v_xor_b32_e32 v171, v171, v204
	v_and_b32_e32 v171, 7, v171
	v_lshlrev_b32_e32 v171, 4, v171
	v_lshl_or_b32 v170, v170, 11, v171
	v_readfirstlane_b32 s30, v204
	s_and_b32 s30, s30, 0x3c0
	s_lshl_b32 s30, s30, 4
	s_mov_b32 s3, 0
	ds_read_b128 v[130:133], v186
	ds_read_b128 v[138:141], v182
	ds_read_b128 v[134:137], v186 offset:4096
	ds_read_b128 v[142:145], v182 offset:4096
	ds_read_b128 v[146:149], v182 offset:8192
	ds_read_b128 v[150:153], v182 offset:12288
	s_add_u32 m0, s30, 0x8000
	s_nop 0
	global_load_lds_dwordx4 v170, s[6:7]
	s_add_u32 m0, s30, 0x18000
	s_nop 0
	global_load_lds_dwordx4 v170, s[22:23]
	s_add_u32 m0, s30, 0xa000
	s_nop 0
	global_load_lds_dwordx4 v170, s[8:9]
	s_add_u32 m0, s30, 0x1a000
	s_nop 0
	global_load_lds_dwordx4 v170, s[24:25]
	s_add_u32 m0, s30, 0xc000
	s_nop 0
	global_load_lds_dwordx4 v170, s[10:11]
	s_add_u32 m0, s30, 0x1c000
	s_nop 0
	global_load_lds_dwordx4 v170, s[26:27]
	s_add_u32 m0, s30, 0xe000
	s_nop 0
	global_load_lds_dwordx4 v170, s[12:13]
	s_add_u32 m0, s30, 0x1e000
	s_nop 0
	global_load_lds_dwordx4 v170, s[28:29]
	s_branch .Lg_aout_mid
.Lg_aout_top:
	ds_read_b128 v[130:133], v186
	ds_read_b128 v[138:141], v182
	ds_read_b128 v[134:137], v186 offset:4096
	ds_read_b128 v[142:145], v182 offset:4096
	ds_read_b128 v[146:149], v182 offset:8192
	ds_read_b128 v[150:153], v182 offset:12288
	s_add_u32 m0, s30, 0x8000
	v_mfma_f32_32x32x16_bf16 v[82:97], v[154:157], v[162:165], v[82:97]
	global_load_lds_dwordx4 v170, s[6:7]
	s_add_u32 m0, s30, 0x18000
	v_mfma_f32_32x32x16_bf16 v[114:129], v[158:161], v[162:165], v[114:129]
	global_load_lds_dwordx4 v170, s[22:23]
	s_add_u32 m0, s30, 0xa000
	v_mfma_f32_32x32x16_bf16 v[66:81], v[154:157], v[166:169], v[66:81]
	global_load_lds_dwordx4 v170, s[8:9]
	s_add_u32 m0, s30, 0x1a000
	v_mfma_f32_32x32x16_bf16 v[98:113], v[158:161], v[166:169], v[98:113]
	global_load_lds_dwordx4 v170, s[24:25]
	s_add_u32 m0, s30, 0xc000
	v_mfma_f32_32x32x16_bf16 v[18:33], v[154:157], v[200:203], v[18:33]
	global_load_lds_dwordx4 v170, s[10:11]
	s_add_u32 m0, s30, 0x1c000
	v_mfma_f32_32x32x16_bf16 v[50:65], v[158:161], v[200:203], v[50:65]
	global_load_lds_dwordx4 v170, s[26:27]
	s_add_u32 m0, s30, 0xe000
	v_mfma_f32_32x32x16_bf16 v[2:17], v[154:157], v[216:219], v[2:17]
	global_load_lds_dwordx4 v170, s[12:13]
	s_add_u32 m0, s30, 0x1e000
	v_mfma_f32_32x32x16_bf16 v[34:49], v[158:161], v[216:219], v[34:49]
	global_load_lds_dwordx4 v170, s[28:29]
.Lg_aout_mid:
	ds_read_b128 v[154:157], v187
	ds_read_b128 v[162:165], v183
	ds_read_b128 v[158:161], v187 offset:4096
	ds_read_b128 v[166:169], v183 offset:4096
	ds_read_b128 v[200:203], v183 offset:8192
	ds_read_b128 v[216:219], v183 offset:12288
	s_waitcnt lgkmcnt(6)
	v_mfma_f32_32x32x16_bf16 v[82:97], v[130:133], v[138:141], v[82:97]
	s_add_u32 s6, s6, 0x80
	s_addc_u32 s7, s7, 0
	v_mfma_f32_32x32x16_bf16 v[114:129], v[134:137], v[138:141], v[114:129]
	s_add_u32 s8, s8, 0x80
	s_addc_u32 s9, s9, 0
	v_mfma_f32_32x32x16_bf16 v[66:81], v[130:133], v[142:145], v[66:81]
	s_add_u32 s10, s10, 0x80
	s_addc_u32 s11, s11, 0
	v_mfma_f32_32x32x16_bf16 v[98:113], v[134:137], v[142:145], v[98:113]
	s_add_u32 s12, s12, 0x80
	s_addc_u32 s13, s13, 0
	v_mfma_f32_32x32x16_bf16 v[18:33], v[130:133], v[146:149], v[18:33]
	s_add_u32 s22, s22, 0x80
	s_addc_u32 s23, s23, 0
	v_mfma_f32_32x32x16_bf16 v[50:65], v[134:137], v[146:149], v[50:65]
	s_add_u32 s24, s24, 0x80
	s_addc_u32 s25, s25, 0
	v_mfma_f32_32x32x16_bf16 v[2:17], v[130:133], v[150:153], v[2:17]
	s_add_u32 s26, s26, 0x80
	s_addc_u32 s27, s27, 0
	v_mfma_f32_32x32x16_bf16 v[34:49], v[134:137], v[150:153], v[34:49]
	s_add_u32 s28, s28, 0x80
	s_addc_u32 s29, s29, 0
	ds_read_b128 v[130:133], v192
	ds_read_b128 v[138:141], v184
	ds_read_b128 v[134:137], v192 offset:4096
	ds_read_b128 v[142:145], v184 offset:4096
	ds_read_b128 v[146:149], v184 offset:8192
	ds_read_b128 v[150:153], v184 offset:12288
	s_waitcnt lgkmcnt(6)
	v_mfma_f32_32x32x16_bf16 v[82:97], v[154:157], v[162:165], v[82:97]
	v_mfma_f32_32x32x16_bf16 v[114:129], v[158:161], v[162:165], v[114:129]
	v_mfma_f32_32x32x16_bf16 v[66:81], v[154:157], v[166:169], v[66:81]
	v_mfma_f32_32x32x16_bf16 v[98:113], v[158:161], v[166:169], v[98:113]
	v_mfma_f32_32x32x16_bf16 v[18:33], v[154:157], v[200:203], v[18:33]
	v_mfma_f32_32x32x16_bf16 v[50:65], v[158:161], v[200:203], v[50:65]
	v_mfma_f32_32x32x16_bf16 v[2:17], v[154:157], v[216:219], v[2:17]
	v_mfma_f32_32x32x16_bf16 v[34:49], v[158:161], v[216:219], v[34:49]
	ds_read_b128 v[154:157], v193
	ds_read_b128 v[162:165], v185
	ds_read_b128 v[158:161], v193 offset:4096
	ds_read_b128 v[166:169], v185 offset:4096
	ds_read_b128 v[200:203], v185 offset:8192
	ds_read_b128 v[216:219], v185 offset:12288
	s_waitcnt lgkmcnt(6)
	v_mfma_f32_32x32x16_bf16 v[82:97], v[130:133], v[138:141], v[82:97]
	v_mfma_f32_32x32x16_bf16 v[114:129], v[134:137], v[138:141], v[114:129]
	v_mfma_f32_32x32x16_bf16 v[66:81], v[130:133], v[142:145], v[66:81]
	v_mfma_f32_32x32x16_bf16 v[98:113], v[134:137], v[142:145], v[98:113]
	v_mfma_f32_32x32x16_bf16 v[18:33], v[130:133], v[146:149], v[18:33]
	v_mfma_f32_32x32x16_bf16 v[50:65], v[134:137], v[146:149], v[50:65]
	v_mfma_f32_32x32x16_bf16 v[2:17], v[130:133], v[150:153], v[2:17]
	v_mfma_f32_32x32x16_bf16 v[34:49], v[134:137], v[150:153], v[34:49]
	s_waitcnt vmcnt(0) lgkmcnt(0)
	s_barrier
	ds_read_b128 v[130:133], v186 offset:32768
	ds_read_b128 v[138:141], v194
	ds_read_b128 v[134:137], v186 offset:36864
	ds_read_b128 v[142:145], v194 offset:4096
	ds_read_b128 v[146:149], v194 offset:8192
	ds_read_b128 v[150:153], v194 offset:12288
	s_cmp_ge_u32 s3, 14
	s_cbranch_scc1 .Lg_aout_nodma
	s_add_u32 m0, s30, 0x0
	v_mfma_f32_32x32x16_bf16 v[82:97], v[154:157], v[162:165], v[82:97]
	global_load_lds_dwordx4 v170, s[6:7]
	s_add_u32 m0, s30, 0x10000
	v_mfma_f32_32x32x16_bf16 v[114:129], v[158:161], v[162:165], v[114:129]
	global_load_lds_dwordx4 v170, s[22:23]
	s_add_u32 m0, s30, 0x2000
	v_mfma_f32_32x32x16_bf16 v[66:81], v[154:157], v[166:169], v[66:81]
	global_load_lds_dwordx4 v170, s[8:9]
	s_add_u32 m0, s30, 0x12000
	v_mfma_f32_32x32x16_bf16 v[98:113], v[158:161], v[166:169], v[98:113]
	global_load_lds_dwordx4 v170, s[24:25]
	s_add_u32 m0, s30, 0x4000
	v_mfma_f32_32x32x16_bf16 v[18:33], v[154:157], v[200:203], v[18:33]
	global_load_lds_dwordx4 v170, s[10:11]
	s_add_u32 m0, s30, 0x14000
	v_mfma_f32_32x32x16_bf16 v[50:65], v[158:161], v[200:203], v[50:65]
	global_load_lds_dwordx4 v170, s[26:27]
	s_add_u32 m0, s30, 0x6000
	v_mfma_f32_32x32x16_bf16 v[2:17], v[154:157], v[216:219], v[2:17]
	global_load_lds_dwordx4 v170, s[12:13]
	s_add_u32 m0, s30, 0x16000
	v_mfma_f32_32x32x16_bf16 v[34:49], v[158:161], v[216:219], v[34:49]
	global_load_lds_dwordx4 v170, s[28:29]
	s_branch .Lg_aout_join

.Lg_aout_join:
	ds_read_b128 v[154:157], v187 offset:32768
	ds_read_b128 v[162:165], v195
	ds_read_b128 v[158:161], v187 offset:36864
	ds_read_b128 v[166:169], v195 offset:4096
	ds_read_b128 v[200:203], v195 offset:8192
	ds_read_b128 v[216:219], v195 offset:12288
	s_waitcnt lgkmcnt(6)
	v_mfma_f32_32x32x16_bf16 v[82:97], v[130:133], v[138:141], v[82:97]
	s_add_u32 s6, s6, 0x80
	s_addc_u32 s7, s7, 0
	v_mfma_f32_32x32x16_bf16 v[114:129], v[134:137], v[138:141], v[114:129]
	s_add_u32 s8, s8, 0x80
	s_addc_u32 s9, s9, 0
	v_mfma_f32_32x32x16_bf16 v[66:81], v[130:133], v[142:145], v[66:81]
	s_add_u32 s10, s10, 0x80
	s_addc_u32 s11, s11, 0
	v_mfma_f32_32x32x16_bf16 v[98:113], v[134:137], v[142:145], v[98:113]
	s_add_u32 s12, s12, 0x80
	s_addc_u32 s13, s13, 0
	v_mfma_f32_32x32x16_bf16 v[18:33], v[130:133], v[146:149], v[18:33]
	s_add_u32 s22, s22, 0x80
	s_addc_u32 s23, s23, 0
	v_mfma_f32_32x32x16_bf16 v[50:65], v[134:137], v[146:149], v[50:65]
	s_add_u32 s24, s24, 0x80
	s_addc_u32 s25, s25, 0
	v_mfma_f32_32x32x16_bf16 v[2:17], v[130:133], v[150:153], v[2:17]
	s_add_u32 s26, s26, 0x80
	s_addc_u32 s27, s27, 0
	v_mfma_f32_32x32x16_bf16 v[34:49], v[134:137], v[150:153], v[34:49]
	s_add_u32 s28, s28, 0x80
	s_addc_u32 s29, s29, 0
	ds_read_b128 v[130:133], v192 offset:32768
	ds_read_b128 v[138:141], v196
	ds_read_b128 v[134:137], v192 offset:36864
	ds_read_b128 v[142:145], v196 offset:4096
	ds_read_b128 v[146:149], v196 offset:8192
	ds_read_b128 v[150:153], v196 offset:12288
	s_waitcnt lgkmcnt(6)
	v_mfma_f32_32x32x16_bf16 v[82:97], v[154:157], v[162:165], v[82:97]
	v_mfma_f32_32x32x16_bf16 v[114:129], v[158:161], v[162:165], v[114:129]
	v_mfma_f32_32x32x16_bf16 v[66:81], v[154:157], v[166:169], v[66:81]
	v_mfma_f32_32x32x16_bf16 v[98:113], v[158:161], v[166:169], v[98:113]
	v_mfma_f32_32x32x16_bf16 v[18:33], v[154:157], v[200:203], v[18:33]
	v_mfma_f32_32x32x16_bf16 v[50:65], v[158:161], v[200:203], v[50:65]
	v_mfma_f32_32x32x16_bf16 v[2:17], v[154:157], v[216:219], v[2:17]
	v_mfma_f32_32x32x16_bf16 v[34:49], v[158:161], v[216:219], v[34:49]
	ds_read_b128 v[154:157], v193 offset:32768
	ds_read_b128 v[162:165], v197
	ds_read_b128 v[158:161], v193 offset:36864
	ds_read_b128 v[166:169], v197 offset:4096
	ds_read_b128 v[200:203], v197 offset:8192
	ds_read_b128 v[216:219], v197 offset:12288
	s_waitcnt lgkmcnt(6)
	v_mfma_f32_32x32x16_bf16 v[82:97], v[130:133], v[138:141], v[82:97]
	v_mfma_f32_32x32x16_bf16 v[114:129], v[134:137], v[138:141], v[114:129]
	v_mfma_f32_32x32x16_bf16 v[66:81], v[130:133], v[142:145], v[66:81]
	v_mfma_f32_32x32x16_bf16 v[98:113], v[134:137], v[142:145], v[98:113]
	v_mfma_f32_32x32x16_bf16 v[18:33], v[130:133], v[146:149], v[18:33]
	v_mfma_f32_32x32x16_bf16 v[50:65], v[134:137], v[146:149], v[50:65]
	v_mfma_f32_32x32x16_bf16 v[2:17], v[130:133], v[150:153], v[2:17]
	v_mfma_f32_32x32x16_bf16 v[34:49], v[134:137], v[150:153], v[34:49]
	s_waitcnt vmcnt(0) lgkmcnt(0)
	s_barrier
	s_add_i32 s3, s3, 2
	s_cmp_lt_u32 s3, 16
	s_cbranch_scc1 .Lg_aout_top
	v_mfma_f32_32x32x16_bf16 v[82:97], v[154:157], v[162:165], v[82:97]
	v_mfma_f32_32x32x16_bf16 v[114:129], v[158:161], v[162:165], v[114:129]
	v_mfma_f32_32x32x16_bf16 v[66:81], v[154:157], v[166:169], v[66:81]
	v_mfma_f32_32x32x16_bf16 v[98:113], v[158:161], v[166:169], v[98:113]
	v_mfma_f32_32x32x16_bf16 v[18:33], v[154:157], v[200:203], v[18:33]
	v_mfma_f32_32x32x16_bf16 v[50:65], v[158:161], v[200:203], v[50:65]
	v_mfma_f32_32x32x16_bf16 v[2:17], v[154:157], v[216:219], v[2:17]
	v_mfma_f32_32x32x16_bf16 v[34:49], v[158:161], v[216:219], v[34:49]
	s_nop 7
	s_nop 7
	s_branch .LBB0_1526

.LBB0_1604:
	s_or_b64 exec, exec, s[10:11]
	v_readlane_b32 s12, v250, 9
	v_readlane_b32 s14, v250, 11
	v_readlane_b32 s15, v250, 12
	s_add_u32 s8, s14, s8
	s_addc_u32 s9, s15, s9
	v_readlane_b32 s5, v252, 57
	s_add_u32 s10, s5, s0
	v_readlane_b32 s5, v252, 58
	s_addc_u32 s11, s5, s1
	v_readlane_b32 s5, v252, 59
	v_readlane_b32 s13, v250, 10
	s_add_u32 s12, s5, s0
	v_readlane_b32 s5, v252, 60
	s_addc_u32 s13, s5, s1
	v_readlane_b32 s5, v252, 61
	s_add_u32 s14, s5, s0
	v_readlane_b32 s5, v252, 62
	s_addc_u32 s15, s5, s1
	v_readlane_b32 s5, v252, 63
	s_add_u32 s16, s5, s0
	v_readlane_b32 s5, v251, 0
	s_addc_u32 s17, s5, s1
	v_readlane_b32 s5, v251, 1
	s_add_u32 s18, s5, s0
	v_readlane_b32 s5, v251, 2
	s_addc_u32 s19, s5, s1
	v_readlane_b32 s5, v251, 3
	s_add_u32 s20, s5, s0
	v_readlane_b32 s5, v251, 4
	s_addc_u32 s21, s5, s1
	v_readlane_b32 s5, v251, 5
	s_add_u32 s22, s5, s0
	v_readlane_b32 s5, v251, 6
	s_addc_u32 s23, s5, s1
	v_readlane_b32 s5, v251, 7
	s_add_u32 s24, s5, s0
	v_readlane_b32 s0, v251, 8
	v_mov_b32_e32 v98, 0
	s_addc_u32 s25, s0, s1
	s_mov_b32 s5, 0
	v_mov_b32_e32 v99, v98
	v_mov_b32_e32 v100, v98
	v_mov_b32_e32 v101, v98
	v_mov_b32_e32 v102, v98
	v_mov_b32_e32 v103, v98
	v_mov_b32_e32 v104, v98
	v_mov_b32_e32 v105, v98
	v_mov_b32_e32 v106, v98
	v_mov_b32_e32 v107, v98
	v_mov_b32_e32 v108, v98
	v_mov_b32_e32 v109, v98
	v_mov_b32_e32 v110, v98
	v_mov_b32_e32 v111, v98
	v_mov_b32_e32 v112, v98
	v_mov_b32_e32 v113, v98
	v_mov_b32_e32 v82, v98
	v_mov_b32_e32 v83, v98
	v_mov_b32_e32 v84, v98
	v_mov_b32_e32 v85, v98
	v_mov_b32_e32 v86, v98
	v_mov_b32_e32 v87, v98
	v_mov_b32_e32 v88, v98
	v_mov_b32_e32 v89, v98
	v_mov_b32_e32 v90, v98
	v_mov_b32_e32 v91, v98
	v_mov_b32_e32 v92, v98
	v_mov_b32_e32 v93, v98
	v_mov_b32_e32 v94, v98
	v_mov_b32_e32 v95, v98
	v_mov_b32_e32 v96, v98
	v_mov_b32_e32 v97, v98
	v_mov_b32_e32 v50, v98
	v_mov_b32_e32 v51, v98
	v_mov_b32_e32 v52, v98
	v_mov_b32_e32 v53, v98
	v_mov_b32_e32 v54, v98
	v_mov_b32_e32 v55, v98
	v_mov_b32_e32 v56, v98
	v_mov_b32_e32 v57, v98
	v_mov_b32_e32 v58, v98
	v_mov_b32_e32 v59, v98
	v_mov_b32_e32 v60, v98
	v_mov_b32_e32 v61, v98
	v_mov_b32_e32 v62, v98
	v_mov_b32_e32 v63, v98
	v_mov_b32_e32 v64, v98
	v_mov_b32_e32 v65, v98
	v_mov_b32_e32 v18, v98
	v_mov_b32_e32 v19, v98
	v_mov_b32_e32 v20, v98
	v_mov_b32_e32 v21, v98
	v_mov_b32_e32 v22, v98
	v_mov_b32_e32 v23, v98
	v_mov_b32_e32 v24, v98
	v_mov_b32_e32 v25, v98
	v_mov_b32_e32 v26, v98
	v_mov_b32_e32 v27, v98
	v_mov_b32_e32 v28, v98
	v_mov_b32_e32 v29, v98
	v_mov_b32_e32 v30, v98
	v_mov_b32_e32 v31, v98
	v_mov_b32_e32 v32, v98
	v_mov_b32_e32 v33, v98
	v_mov_b32_e32 v114, v98
	v_mov_b32_e32 v115, v98
	v_mov_b32_e32 v116, v98
	v_mov_b32_e32 v117, v98
	v_mov_b32_e32 v118, v98
	v_mov_b32_e32 v119, v98
	v_mov_b32_e32 v120, v98
	v_mov_b32_e32 v121, v98
	v_mov_b32_e32 v122, v98
	v_mov_b32_e32 v123, v98
	v_mov_b32_e32 v124, v98
	v_mov_b32_e32 v125, v98
	v_mov_b32_e32 v126, v98
	v_mov_b32_e32 v127, v98
	v_mov_b32_e32 v128, v98
	v_mov_b32_e32 v129, v98
	v_mov_b32_e32 v66, v98
	v_mov_b32_e32 v67, v98
	v_mov_b32_e32 v68, v98
	v_mov_b32_e32 v69, v98
	v_mov_b32_e32 v70, v98
	v_mov_b32_e32 v71, v98
	v_mov_b32_e32 v72, v98
	v_mov_b32_e32 v73, v98
	v_mov_b32_e32 v74, v98
	v_mov_b32_e32 v75, v98
	v_mov_b32_e32 v76, v98
	v_mov_b32_e32 v77, v98
	v_mov_b32_e32 v78, v98
	v_mov_b32_e32 v79, v98
	v_mov_b32_e32 v80, v98
	v_mov_b32_e32 v81, v98
	v_mov_b32_e32 v34, v98
	v_mov_b32_e32 v35, v98
	v_mov_b32_e32 v36, v98
	v_mov_b32_e32 v37, v98
	v_mov_b32_e32 v38, v98
	v_mov_b32_e32 v39, v98
	v_mov_b32_e32 v40, v98
	v_mov_b32_e32 v41, v98
	v_mov_b32_e32 v42, v98
	v_mov_b32_e32 v43, v98
	v_mov_b32_e32 v44, v98
	v_mov_b32_e32 v45, v98
	v_mov_b32_e32 v46, v98
	v_mov_b32_e32 v47, v98
	v_mov_b32_e32 v48, v98
	v_mov_b32_e32 v49, v98
	v_mov_b32_e32 v2, v98
	v_mov_b32_e32 v3, v98
	v_mov_b32_e32 v4, v98
	v_mov_b32_e32 v5, v98
	v_mov_b32_e32 v6, v98
	v_mov_b32_e32 v7, v98
	v_mov_b32_e32 v8, v98
	v_mov_b32_e32 v9, v98
	v_mov_b32_e32 v10, v98
	v_mov_b32_e32 v11, v98
	v_mov_b32_e32 v12, v98
	v_mov_b32_e32 v13, v98
	v_mov_b32_e32 v14, v98
	v_mov_b32_e32 v15, v98
	v_mov_b32_e32 v16, v98
	v_mov_b32_e32 v17, v98
	s_mov_b64 s[26:27], s[8:9]
	s_mov_b32 s8, s10
	s_mov_b32 s9, s11
	s_add_u32 s10, s8, 0x20000
	s_addc_u32 s11, s9, 0
	s_add_u32 s12, s8, 0x40000
	s_addc_u32 s13, s9, 0
	s_add_u32 s14, s8, 0x60000
	s_addc_u32 s15, s9, 0
	s_add_u32 s16, s26, 0x5800080
	s_addc_u32 s17, s27, 0
	s_add_u32 s18, s16, 0x20000
	s_addc_u32 s19, s17, 0
	s_add_u32 s20, s16, 0x40000
	s_addc_u32 s21, s17, 0
	s_add_u32 s22, s16, 0x60000
	s_addc_u32 s23, s17, 0
	v_lshrrev_b32_e32 v170, 3, v204
	v_lshrrev_b32_e32 v171, 4, v204
	v_xor_b32_e32 v171, v171, v204
	v_and_b32_e32 v171, 7, v171
	v_lshlrev_b32_e32 v171, 4, v171
	v_lshl_or_b32 v170, v170, 11, v171
	v_readfirstlane_b32 s24, v204
	s_and_b32 s24, s24, 0x3c0
	s_lshl_b32 s24, s24, 4
	s_mov_b32 s5, 0
	ds_read_b128 v[130:133], v186
	ds_read_b128 v[138:141], v181
	ds_read_b128 v[134:137], v186 offset:4096
	ds_read_b128 v[142:145], v181 offset:4096
	ds_read_b128 v[146:149], v181 offset:8192
	ds_read_b128 v[150:153], v181 offset:12288
	s_add_u32 m0, s24, 0x8000
	s_nop 0
	global_load_lds_dwordx4 v170, s[8:9]
	s_add_u32 m0, s24, 0x18000
	s_nop 0
	global_load_lds_dwordx4 v170, s[16:17]
	s_add_u32 m0, s24, 0xa000
	s_nop 0
	global_load_lds_dwordx4 v170, s[10:11]
	s_add_u32 m0, s24, 0x1a000
	s_nop 0
	global_load_lds_dwordx4 v170, s[18:19]
	s_add_u32 m0, s24, 0xc000
	s_nop 0
	global_load_lds_dwordx4 v170, s[12:13]
	s_add_u32 m0, s24, 0x1c000
	s_nop 0
	global_load_lds_dwordx4 v170, s[20:21]
	s_add_u32 m0, s24, 0xe000
	s_nop 0
	global_load_lds_dwordx4 v170, s[14:15]
	s_add_u32 m0, s24, 0x1e000
	s_nop 0
	global_load_lds_dwordx4 v170, s[22:23]
	s_branch .Lg_mlp1_mid
.Lg_mlp1_top:
	ds_read_b128 v[130:133], v186
	ds_read_b128 v[138:141], v181
	ds_read_b128 v[134:137], v186 offset:4096
	ds_read_b128 v[142:145], v181 offset:4096
	ds_read_b128 v[146:149], v181 offset:8192
	ds_read_b128 v[150:153], v181 offset:12288
	s_add_u32 m0, s24, 0x8000
	v_mfma_f32_32x32x16_bf16 v[98:113], v[154:157], v[162:165], v[98:113]
	global_load_lds_dwordx4 v170, s[8:9]
	s_add_u32 m0, s24, 0x18000
	v_mfma_f32_32x32x16_bf16 v[114:129], v[158:161], v[162:165], v[114:129]
	global_load_lds_dwordx4 v170, s[16:17]
	s_add_u32 m0, s24, 0xa000
	v_mfma_f32_32x32x16_bf16 v[82:97], v[154:157], v[166:169], v[82:97]
	global_load_lds_dwordx4 v170, s[10:11]
	s_add_u32 m0, s24, 0x1a000
	v_mfma_f32_32x32x16_bf16 v[66:81], v[158:161], v[166:169], v[66:81]
	global_load_lds_dwordx4 v170, s[18:19]
	s_add_u32 m0, s24, 0xc000
	v_mfma_f32_32x32x16_bf16 v[50:65], v[154:157], v[196:199], v[50:65]
	global_load_lds_dwordx4 v170, s[12:13]
	s_add_u32 m0, s24, 0x1c000
	v_mfma_f32_32x32x16_bf16 v[34:49], v[158:161], v[196:199], v[34:49]
	global_load_lds_dwordx4 v170, s[20:21]
	s_add_u32 m0, s24, 0xe000
	v_mfma_f32_32x32x16_bf16 v[18:33], v[154:157], v[200:203], v[18:33]
	global_load_lds_dwordx4 v170, s[14:15]
	s_add_u32 m0, s24, 0x1e000
	v_mfma_f32_32x32x16_bf16 v[2:17], v[158:161], v[200:203], v[2:17]
	global_load_lds_dwordx4 v170, s[22:23]
.Lg_mlp1_mid:
	ds_read_b128 v[154:157], v187
	ds_read_b128 v[162:165], v182
	ds_read_b128 v[158:161], v187 offset:4096
	ds_read_b128 v[166:169], v182 offset:4096
	ds_read_b128 v[196:199], v182 offset:8192
	ds_read_b128 v[200:203], v182 offset:12288
	s_waitcnt lgkmcnt(6)
	v_mfma_f32_32x32x16_bf16 v[98:113], v[130:133], v[138:141], v[98:113]
	s_add_u32 s8, s8, 0x80
	s_addc_u32 s9, s9, 0
	v_mfma_f32_32x32x16_bf16 v[114:129], v[134:137], v[138:141], v[114:129]
	s_add_u32 s10, s10, 0x80
	s_addc_u32 s11, s11, 0
	v_mfma_f32_32x32x16_bf16 v[82:97], v[130:133], v[142:145], v[82:97]
	s_add_u32 s12, s12, 0x80
	s_addc_u32 s13, s13, 0
	v_mfma_f32_32x32x16_bf16 v[66:81], v[134:137], v[142:145], v[66:81]
	s_add_u32 s14, s14, 0x80
	s_addc_u32 s15, s15, 0
	v_mfma_f32_32x32x16_bf16 v[50:65], v[130:133], v[146:149], v[50:65]
	s_add_u32 s16, s16, 0x80
	s_addc_u32 s17, s17, 0
	v_mfma_f32_32x32x16_bf16 v[34:49], v[134:137], v[146:149], v[34:49]
	s_add_u32 s18, s18, 0x80
	s_addc_u32 s19, s19, 0
	v_mfma_f32_32x32x16_bf16 v[18:33], v[130:133], v[150:153], v[18:33]
	s_add_u32 s20, s20, 0x80
	s_addc_u32 s21, s21, 0
	v_mfma_f32_32x32x16_bf16 v[2:17], v[134:137], v[150:153], v[2:17]
	s_add_u32 s22, s22, 0x80
	s_addc_u32 s23, s23, 0
	ds_read_b128 v[130:133], v188
	ds_read_b128 v[138:141], v183
	ds_read_b128 v[134:137], v188 offset:4096
	ds_read_b128 v[142:145], v183 offset:4096
	ds_read_b128 v[146:149], v183 offset:8192
	ds_read_b128 v[150:153], v183 offset:12288
	s_waitcnt lgkmcnt(6)
	v_mfma_f32_32x32x16_bf16 v[98:113], v[154:157], v[162:165], v[98:113]
	v_mfma_f32_32x32x16_bf16 v[114:129], v[158:161], v[162:165], v[114:129]
	v_mfma_f32_32x32x16_bf16 v[82:97], v[154:157], v[166:169], v[82:97]
	v_mfma_f32_32x32x16_bf16 v[66:81], v[158:161], v[166:169], v[66:81]
	v_mfma_f32_32x32x16_bf16 v[50:65], v[154:157], v[196:199], v[50:65]
	v_mfma_f32_32x32x16_bf16 v[34:49], v[158:161], v[196:199], v[34:49]
	v_mfma_f32_32x32x16_bf16 v[18:33], v[154:157], v[200:203], v[18:33]
	v_mfma_f32_32x32x16_bf16 v[2:17], v[158:161], v[200:203], v[2:17]
	ds_read_b128 v[154:157], v189
	ds_read_b128 v[162:165], v184
	ds_read_b128 v[158:161], v189 offset:4096
	ds_read_b128 v[166:169], v184 offset:4096
	ds_read_b128 v[196:199], v184 offset:8192
	ds_read_b128 v[200:203], v184 offset:12288
	s_waitcnt lgkmcnt(6)
	v_mfma_f32_32x32x16_bf16 v[98:113], v[130:133], v[138:141], v[98:113]
	v_mfma_f32_32x32x16_bf16 v[114:129], v[134:137], v[138:141], v[114:129]
	v_mfma_f32_32x32x16_bf16 v[82:97], v[130:133], v[142:145], v[82:97]
	v_mfma_f32_32x32x16_bf16 v[66:81], v[134:137], v[142:145], v[66:81]
	v_mfma_f32_32x32x16_bf16 v[50:65], v[130:133], v[146:149], v[50:65]
	v_mfma_f32_32x32x16_bf16 v[34:49], v[134:137], v[146:149], v[34:49]
	v_mfma_f32_32x32x16_bf16 v[18:33], v[130:133], v[150:153], v[18:33]
	v_mfma_f32_32x32x16_bf16 v[2:17], v[134:137], v[150:153], v[2:17]
	s_waitcnt vmcnt(0) lgkmcnt(0)
	s_barrier
	ds_read_b128 v[130:133], v186 offset:32768
	ds_read_b128 v[138:141], v190
	ds_read_b128 v[134:137], v186 offset:36864
	ds_read_b128 v[142:145], v190 offset:4096
	ds_read_b128 v[146:149], v190 offset:8192
	ds_read_b128 v[150:153], v190 offset:12288
	s_cmp_ge_u32 s5, 14
	s_cbranch_scc1 .Lg_mlp1_nodma
	s_add_u32 m0, s24, 0x0
	v_mfma_f32_32x32x16_bf16 v[98:113], v[154:157], v[162:165], v[98:113]
	global_load_lds_dwordx4 v170, s[8:9]
	s_add_u32 m0, s24, 0x10000
	v_mfma_f32_32x32x16_bf16 v[114:129], v[158:161], v[162:165], v[114:129]
	global_load_lds_dwordx4 v170, s[16:17]
	s_add_u32 m0, s24, 0x2000
	v_mfma_f32_32x32x16_bf16 v[82:97], v[154:157], v[166:169], v[82:97]
	global_load_lds_dwordx4 v170, s[10:11]
	s_add_u32 m0, s24, 0x12000
	v_mfma_f32_32x32x16_bf16 v[66:81], v[158:161], v[166:169], v[66:81]
	global_load_lds_dwordx4 v170, s[18:19]
	s_add_u32 m0, s24, 0x4000
	v_mfma_f32_32x32x16_bf16 v[50:65], v[154:157], v[196:199], v[50:65]
	global_load_lds_dwordx4 v170, s[12:13]
	s_add_u32 m0, s24, 0x14000
	v_mfma_f32_32x32x16_bf16 v[34:49], v[158:161], v[196:199], v[34:49]
	global_load_lds_dwordx4 v170, s[20:21]
	s_add_u32 m0, s24, 0x6000
	v_mfma_f32_32x32x16_bf16 v[18:33], v[154:157], v[200:203], v[18:33]
	global_load_lds_dwordx4 v170, s[14:15]
	s_add_u32 m0, s24, 0x16000
	v_mfma_f32_32x32x16_bf16 v[2:17], v[158:161], v[200:203], v[2:17]
	global_load_lds_dwordx4 v170, s[22:23]
	s_branch .Lg_mlp1_join
.Lg_mlp1_nodma:
	v_mfma_f32_32x32x16_bf16 v[98:113], v[154:157], v[162:165], v[98:113]
	v_mfma_f32_32x32x16_bf16 v[114:129], v[158:161], v[162:165], v[114:129]
	v_mfma_f32_32x32x16_bf16 v[82:97], v[154:157], v[166:169], v[82:97]
	v_mfma_f32_32x32x16_bf16 v[66:81], v[158:161], v[166:169], v[66:81]
	v_mfma_f32_32x32x16_bf16 v[50:65], v[154:157], v[196:199], v[50:65]
	v_mfma_f32_32x32x16_bf16 v[34:49], v[158:161], v[196:199], v[34:49]
	v_mfma_f32_32x32x16_bf16 v[18:33], v[154:157], v[200:203], v[18:33]
	v_mfma_f32_32x32x16_bf16 v[2:17], v[158:161], v[200:203], v[2:17]
.Lg_mlp1_join:
	ds_read_b128 v[154:157], v187 offset:32768
	ds_read_b128 v[162:165], v191
	ds_read_b128 v[158:161], v187 offset:36864
	ds_read_b128 v[166:169], v191 offset:4096
	ds_read_b128 v[196:199], v191 offset:8192
	ds_read_b128 v[200:203], v191 offset:12288
	s_waitcnt lgkmcnt(6)
	v_mfma_f32_32x32x16_bf16 v[98:113], v[130:133], v[138:141], v[98:113]
	s_add_u32 s8, s8, 0x80
	s_addc_u32 s9, s9, 0
	v_mfma_f32_32x32x16_bf16 v[114:129], v[134:137], v[138:141], v[114:129]
	s_add_u32 s10, s10, 0x80
	s_addc_u32 s11, s11, 0
	v_mfma_f32_32x32x16_bf16 v[82:97], v[130:133], v[142:145], v[82:97]
	s_add_u32 s12, s12, 0x80
	s_addc_u32 s13, s13, 0
	v_mfma_f32_32x32x16_bf16 v[66:81], v[134:137], v[142:145], v[66:81]
	s_add_u32 s14, s14, 0x80
	s_addc_u32 s15, s15, 0
	v_mfma_f32_32x32x16_bf16 v[50:65], v[130:133], v[146:149], v[50:65]
	s_add_u32 s16, s16, 0x80
	s_addc_u32 s17, s17, 0
	v_mfma_f32_32x32x16_bf16 v[34:49], v[134:137], v[146:149], v[34:49]
	s_add_u32 s18, s18, 0x80
	s_addc_u32 s19, s19, 0
	v_mfma_f32_32x32x16_bf16 v[18:33], v[130:133], v[150:153], v[18:33]
	s_add_u32 s20, s20, 0x80
	s_addc_u32 s21, s21, 0
	v_mfma_f32_32x32x16_bf16 v[2:17], v[134:137], v[150:153], v[2:17]
	s_add_u32 s22, s22, 0x80
	s_addc_u32 s23, s23, 0
	ds_read_b128 v[130:133], v188 offset:32768
	ds_read_b128 v[138:141], v192
	ds_read_b128 v[134:137], v188 offset:36864
	ds_read_b128 v[142:145], v192 offset:4096
	ds_read_b128 v[146:149], v192 offset:8192
	ds_read_b128 v[150:153], v192 offset:12288
	s_waitcnt lgkmcnt(6)
	v_mfma_f32_32x32x16_bf16 v[98:113], v[154:157], v[162:165], v[98:113]
	v_mfma_f32_32x32x16_bf16 v[114:129], v[158:161], v[162:165], v[114:129]
	v_mfma_f32_32x32x16_bf16 v[82:97], v[154:157], v[166:169], v[82:97]
	v_mfma_f32_32x32x16_bf16 v[66:81], v[158:161], v[166:169], v[66:81]
	v_mfma_f32_32x32x16_bf16 v[50:65], v[154:157], v[196:199], v[50:65]
	v_mfma_f32_32x32x16_bf16 v[34:49], v[158:161], v[196:199], v[34:49]
	v_mfma_f32_32x32x16_bf16 v[18:33], v[154:157], v[200:203], v[18:33]
	v_mfma_f32_32x32x16_bf16 v[2:17], v[158:161], v[200:203], v[2:17]
	ds_read_b128 v[154:157], v189 offset:32768
	ds_read_b128 v[162:165], v193
	ds_read_b128 v[158:161], v189 offset:36864
	ds_read_b128 v[166:169], v193 offset:4096
	ds_read_b128 v[196:199], v193 offset:8192
	ds_read_b128 v[200:203], v193 offset:12288
	s_waitcnt lgkmcnt(6)
	v_mfma_f32_32x32x16_bf16 v[98:113], v[130:133], v[138:141], v[98:113]
	v_mfma_f32_32x32x16_bf16 v[114:129], v[134:137], v[138:141], v[114:129]
	v_mfma_f32_32x32x16_bf16 v[82:97], v[130:133], v[142:145], v[82:97]
	v_mfma_f32_32x32x16_bf16 v[66:81], v[134:137], v[142:145], v[66:81]
	v_mfma_f32_32x32x16_bf16 v[50:65], v[130:133], v[146:149], v[50:65]
	v_mfma_f32_32x32x16_bf16 v[34:49], v[134:137], v[146:149], v[34:49]
	v_mfma_f32_32x32x16_bf16 v[18:33], v[130:133], v[150:153], v[18:33]
	v_mfma_f32_32x32x16_bf16 v[2:17], v[134:137], v[150:153], v[2:17]
	s_waitcnt vmcnt(0) lgkmcnt(0)
	s_barrier
	s_add_i32 s5, s5, 2
	s_cmp_lt_u32 s5, 16
	s_cbranch_scc1 .Lg_mlp1_top
	v_mfma_f32_32x32x16_bf16 v[98:113], v[154:157], v[162:165], v[98:113]
	v_mfma_f32_32x32x16_bf16 v[114:129], v[158:161], v[162:165], v[114:129]
	v_mfma_f32_32x32x16_bf16 v[82:97], v[154:157], v[166:169], v[82:97]
	v_mfma_f32_32x32x16_bf16 v[66:81], v[158:161], v[166:169], v[66:81]
	v_mfma_f32_32x32x16_bf16 v[50:65], v[154:157], v[196:199], v[50:65]
	v_mfma_f32_32x32x16_bf16 v[34:49], v[158:161], v[196:199], v[34:49]
	v_mfma_f32_32x32x16_bf16 v[18:33], v[154:157], v[200:203], v[18:33]
	v_mfma_f32_32x32x16_bf16 v[2:17], v[158:161], v[200:203], v[2:17]
	s_nop 7
	s_nop 7
	s_branch .LBB0_1601

.LBB0_1678:
	s_bfe_u32 s4, s30, 0x20003
	s_lshr_b32 s0, s30, 5
	s_lshl_b32 s0, s0, 3
	s_and_b32 s1, s30, 7
	s_add_i32 s0, s0, s1
	s_lshl_b32 s2, s0, 8
	s_ashr_i32 s3, s2, 31
	s_ashr_i32 s5, s4, 31
	s_lshl_b64 s[0:1], s[4:5], 21
	s_lshl_b64 s[6:7], s[2:3], 13
	v_readlane_b32 s8, v250, 48
	v_readlane_b32 s9, v250, 49
	s_add_u32 s8, s8, s6
	v_mov_b32_e32 v34, v172
	s_addc_u32 s9, s9, s7
	s_add_u32 s10, s28, s0
	v_lshlrev_b32_e32 v0, 4, v34
	v_ashrrev_i32_e32 v35, 3, v34
	v_and_b32_e32 v0, 0x70, v0
	s_addc_u32 s11, s29, s1
	v_lshl_or_b32 v0, v35, 13, v0
	v_lshl_add_u64 v[26:27], s[10:11], 0, v[0:1]
	s_mov_b32 s3, 0x80000
	v_add_co_u32_e32 v10, vcc, s3, v26
	v_lshl_add_u64 v[28:29], s[8:9], 0, v[0:1]
	s_nop 0
	v_addc_co_u32_e32 v11, vcc, 0, v27, vcc
	v_add_co_u32_e32 v14, vcc, s3, v28
	s_mov_b32 s3, 0x100000
	s_nop 0
	v_addc_co_u32_e32 v15, vcc, 0, v29, vcc
	v_add_co_u32_e32 v18, vcc, s3, v26
	global_load_dwordx4 v[2:5], v0, s[10:11]
	global_load_dwordx4 v[6:9], v0, s[8:9]
	v_addc_co_u32_e32 v19, vcc, 0, v27, vcc
	v_add_co_u32_e32 v22, vcc, s3, v28
	s_mov_b32 s3, 0x180000
	s_nop 0
	v_addc_co_u32_e32 v23, vcc, 0, v29, vcc
	v_add_co_u32_e32 v26, vcc, s3, v26
	global_load_dwordx4 v[10:13], v[10:11], off
	s_nop 0
	global_load_dwordx4 v[14:17], v[14:15], off
	v_addc_co_u32_e32 v27, vcc, 0, v27, vcc
	v_add_co_u32_e32 v30, vcc, s3, v28
	global_load_dwordx4 v[18:21], v[18:19], off
	s_nop 0
	global_load_dwordx4 v[22:25], v[22:23], off
	v_addc_co_u32_e32 v31, vcc, 0, v29, vcc
	global_load_dwordx4 v[26:29], v[26:27], off
	s_nop 0
	global_load_dwordx4 v[30:33], v[30:31], off
	v_readlane_b32 s8, v250, 9
	v_readlane_b32 s10, v250, 11
	v_readlane_b32 s11, v250, 12
	s_add_u32 s6, s10, s6
	s_addc_u32 s7, s11, s7
	v_readlane_b32 s5, v251, 9
	v_readlane_b32 s9, v250, 10
	s_add_u32 s8, s5, s0
	v_readlane_b32 s5, v251, 10
	s_addc_u32 s9, s5, s1
	v_readlane_b32 s5, v251, 11
	s_add_u32 s10, s5, s0
	v_readlane_b32 s5, v251, 12
	s_addc_u32 s11, s5, s1
	v_readlane_b32 s5, v251, 13
	s_add_u32 s12, s5, s0
	v_readlane_b32 s5, v251, 14
	s_addc_u32 s13, s5, s1
	v_readlane_b32 s5, v251, 15
	s_add_u32 s14, s5, s0
	v_readlane_b32 s5, v251, 16
	s_addc_u32 s15, s5, s1
	v_readlane_b32 s5, v251, 17
	s_add_u32 s16, s5, s0
	v_readlane_b32 s5, v251, 18
	s_addc_u32 s17, s5, s1
	v_readlane_b32 s5, v251, 19
	s_add_u32 s18, s5, s0
	v_readlane_b32 s5, v251, 20
	v_lshrrev_b32_e32 v36, 1, v35
	s_addc_u32 s19, s5, s1
	v_readlane_b32 s5, v251, 21
	v_xor_b32_e32 v34, v36, v34
	s_add_u32 s20, s5, s0
	v_readlane_b32 s5, v251, 22
	v_lshlrev_b32_e32 v35, 7, v35
	v_lshlrev_b32_e32 v34, 4, v34
	s_addc_u32 s21, s5, s1
	v_readlane_b32 s5, v251, 23
	v_mov_b32_e32 v66, 0
	v_and_or_b32 v192, v34, s55, v35
	s_add_u32 s22, s5, s0
	v_readlane_b32 s0, v251, 24
	s_mov_b32 s3, 0
	v_mov_b32_e32 v67, v66
	v_mov_b32_e32 v68, v66
	v_add_u32_e32 v193, 0x10000, v192
	s_addc_u32 s23, s0, s1
	s_waitcnt vmcnt(7)
	ds_write_b128 v192, v[2:5]
	s_waitcnt vmcnt(6)
	ds_write_b128 v193, v[6:9]
	s_waitcnt vmcnt(5)
	ds_write_b128 v192, v[10:13] offset:8192
	s_waitcnt vmcnt(4)
	ds_write_b128 v193, v[14:17] offset:8192
	s_waitcnt vmcnt(3)
	ds_write_b128 v192, v[18:21] offset:16384
	s_waitcnt vmcnt(2)
	ds_write_b128 v193, v[22:25] offset:16384
	s_waitcnt vmcnt(1)
	ds_write_b128 v192, v[26:29] offset:24576
	s_waitcnt vmcnt(0)
	ds_write_b128 v193, v[30:33] offset:24576
	v_mov_b32_e32 v69, v66
	v_mov_b32_e32 v70, v66
	v_mov_b32_e32 v71, v66
	v_mov_b32_e32 v72, v66
	v_mov_b32_e32 v73, v66
	v_mov_b32_e32 v74, v66
	v_mov_b32_e32 v75, v66
	v_mov_b32_e32 v76, v66
	v_mov_b32_e32 v77, v66
	v_mov_b32_e32 v78, v66
	v_mov_b32_e32 v79, v66
	v_mov_b32_e32 v80, v66
	v_mov_b32_e32 v81, v66
	v_mov_b32_e32 v82, v66
	v_mov_b32_e32 v83, v66
	v_mov_b32_e32 v84, v66
	v_mov_b32_e32 v85, v66
	v_mov_b32_e32 v86, v66
	v_mov_b32_e32 v87, v66
	v_mov_b32_e32 v88, v66
	v_mov_b32_e32 v89, v66
	v_mov_b32_e32 v90, v66
	v_mov_b32_e32 v91, v66
	v_mov_b32_e32 v92, v66
	v_mov_b32_e32 v93, v66
	v_mov_b32_e32 v94, v66
	v_mov_b32_e32 v95, v66
	v_mov_b32_e32 v96, v66
	v_mov_b32_e32 v97, v66
	v_mov_b32_e32 v18, v66
	v_mov_b32_e32 v19, v66
	v_mov_b32_e32 v20, v66
	v_mov_b32_e32 v21, v66
	v_mov_b32_e32 v22, v66
	v_mov_b32_e32 v23, v66
	v_mov_b32_e32 v24, v66
	v_mov_b32_e32 v25, v66
	v_mov_b32_e32 v26, v66
	v_mov_b32_e32 v27, v66
	v_mov_b32_e32 v28, v66
	v_mov_b32_e32 v29, v66
	v_mov_b32_e32 v30, v66
	v_mov_b32_e32 v31, v66
	v_mov_b32_e32 v32, v66
	v_mov_b32_e32 v33, v66
	v_mov_b32_e32 v2, v66
	v_mov_b32_e32 v3, v66
	v_mov_b32_e32 v4, v66
	v_mov_b32_e32 v5, v66
	v_mov_b32_e32 v6, v66
	v_mov_b32_e32 v7, v66
	v_mov_b32_e32 v8, v66
	v_mov_b32_e32 v9, v66
	v_mov_b32_e32 v10, v66
	v_mov_b32_e32 v11, v66
	v_mov_b32_e32 v12, v66
	v_mov_b32_e32 v13, v66
	v_mov_b32_e32 v14, v66
	v_mov_b32_e32 v15, v66
	v_mov_b32_e32 v16, v66
	v_mov_b32_e32 v17, v66
	v_mov_b32_e32 v114, v66
	v_mov_b32_e32 v115, v66
	v_mov_b32_e32 v116, v66
	v_mov_b32_e32 v117, v66
	v_mov_b32_e32 v118, v66
	v_mov_b32_e32 v119, v66
	v_mov_b32_e32 v120, v66
	v_mov_b32_e32 v121, v66
	v_mov_b32_e32 v122, v66
	v_mov_b32_e32 v123, v66
	v_mov_b32_e32 v124, v66
	v_mov_b32_e32 v125, v66
	v_mov_b32_e32 v126, v66
	v_mov_b32_e32 v127, v66
	v_mov_b32_e32 v128, v66
	v_mov_b32_e32 v129, v66
	v_mov_b32_e32 v98, v66
	v_mov_b32_e32 v99, v66
	v_mov_b32_e32 v100, v66
	v_mov_b32_e32 v101, v66
	v_mov_b32_e32 v102, v66
	v_mov_b32_e32 v103, v66
	v_mov_b32_e32 v104, v66
	v_mov_b32_e32 v105, v66
	v_mov_b32_e32 v106, v66
	v_mov_b32_e32 v107, v66
	v_mov_b32_e32 v108, v66
	v_mov_b32_e32 v109, v66
	v_mov_b32_e32 v110, v66
	v_mov_b32_e32 v111, v66
	v_mov_b32_e32 v112, v66
	v_mov_b32_e32 v113, v66
	v_mov_b32_e32 v50, v66
	v_mov_b32_e32 v51, v66
	v_mov_b32_e32 v52, v66
	v_mov_b32_e32 v53, v66
	v_mov_b32_e32 v54, v66
	v_mov_b32_e32 v55, v66
	v_mov_b32_e32 v56, v66
	v_mov_b32_e32 v57, v66
	v_mov_b32_e32 v58, v66
	v_mov_b32_e32 v59, v66
	v_mov_b32_e32 v60, v66
	v_mov_b32_e32 v61, v66
	v_mov_b32_e32 v62, v66
	v_mov_b32_e32 v63, v66
	v_mov_b32_e32 v64, v66
	v_mov_b32_e32 v65, v66
	v_mov_b32_e32 v34, v66
	v_mov_b32_e32 v35, v66
	v_mov_b32_e32 v36, v66
	v_mov_b32_e32 v37, v66
	v_mov_b32_e32 v38, v66
	v_mov_b32_e32 v39, v66
	v_mov_b32_e32 v40, v66
	v_mov_b32_e32 v41, v66
	v_mov_b32_e32 v42, v66
	v_mov_b32_e32 v43, v66
	v_mov_b32_e32 v44, v66
	v_mov_b32_e32 v45, v66
	v_mov_b32_e32 v46, v66
	v_mov_b32_e32 v47, v66
	v_mov_b32_e32 v48, v66
	v_mov_b32_e32 v49, v66
	s_waitcnt lgkmcnt(0)
	s_barrier
	s_add_u32 s10, s8, 0x80000
	s_addc_u32 s11, s9, 0
	s_add_u32 s12, s8, 0x100000
	s_addc_u32 s13, s9, 0
	s_add_u32 s14, s8, 0x180000
	s_addc_u32 s15, s9, 0
	s_add_u32 s16, s6, 0x7800080
	s_addc_u32 s17, s7, 0
	s_add_u32 s18, s16, 0x80000
	s_addc_u32 s19, s17, 0
	s_add_u32 s20, s16, 0x100000
	s_addc_u32 s21, s17, 0
	s_add_u32 s22, s16, 0x180000
	s_addc_u32 s23, s17, 0
	v_lshrrev_b32_e32 v170, 3, v204
	v_lshrrev_b32_e32 v171, 4, v204
	v_xor_b32_e32 v171, v171, v204
	v_and_b32_e32 v171, 7, v171
	v_lshlrev_b32_e32 v171, 4, v171
	v_lshl_or_b32 v170, v170, 13, v171
	v_readfirstlane_b32 s24, v204
	s_and_b32 s24, s24, 0x3c0
	s_lshl_b32 s24, s24, 4
	s_mov_b32 s3, 0
	ds_read_b128 v[130:133], v184
	ds_read_b128 v[138:141], v180
	ds_read_b128 v[134:137], v184 offset:4096
	ds_read_b128 v[142:145], v180 offset:4096
	ds_read_b128 v[146:149], v180 offset:8192
	ds_read_b128 v[150:153], v180 offset:12288
	s_add_u32 m0, s24, 0x8000
	s_nop 0
	global_load_lds_dwordx4 v170, s[8:9]
	s_add_u32 m0, s24, 0x18000
	s_nop 0
	global_load_lds_dwordx4 v170, s[16:17]
	s_add_u32 m0, s24, 0xa000
	s_nop 0
	global_load_lds_dwordx4 v170, s[10:11]
	s_add_u32 m0, s24, 0x1a000
	s_nop 0
	global_load_lds_dwordx4 v170, s[18:19]
	s_add_u32 m0, s24, 0xc000
	s_nop 0
	global_load_lds_dwordx4 v170, s[12:13]
	s_add_u32 m0, s24, 0x1c000
	s_nop 0
	global_load_lds_dwordx4 v170, s[20:21]
	s_add_u32 m0, s24, 0xe000
	s_nop 0
	global_load_lds_dwordx4 v170, s[14:15]
	s_add_u32 m0, s24, 0x1e000
	s_nop 0
	global_load_lds_dwordx4 v170, s[22:23]
	s_branch .Lg_mlp2_mid
.Lg_mlp2_top:
	ds_read_b128 v[130:133], v184
	ds_read_b128 v[138:141], v180
	ds_read_b128 v[134:137], v184 offset:4096
	ds_read_b128 v[142:145], v180 offset:4096
	ds_read_b128 v[146:149], v180 offset:8192
	ds_read_b128 v[150:153], v180 offset:12288
	s_add_u32 m0, s24, 0x8000
	v_mfma_f32_32x32x16_bf16 v[66:81], v[154:157], v[162:165], v[66:81]
	global_load_lds_dwordx4 v170, s[8:9]
	s_add_u32 m0, s24, 0x18000
	v_mfma_f32_32x32x16_bf16 v[114:129], v[158:161], v[162:165], v[114:129]
	global_load_lds_dwordx4 v170, s[16:17]
	s_add_u32 m0, s24, 0xa000
	v_mfma_f32_32x32x16_bf16 v[82:97], v[154:157], v[166:169], v[82:97]
	global_load_lds_dwordx4 v170, s[10:11]
	s_add_u32 m0, s24, 0x1a000
	v_mfma_f32_32x32x16_bf16 v[98:113], v[158:161], v[166:169], v[98:113]
	global_load_lds_dwordx4 v170, s[18:19]
	s_add_u32 m0, s24, 0xc000
	v_mfma_f32_32x32x16_bf16 v[18:33], v[154:157], v[194:197], v[18:33]
	global_load_lds_dwordx4 v170, s[12:13]
	s_add_u32 m0, s24, 0x1c000
	v_mfma_f32_32x32x16_bf16 v[50:65], v[158:161], v[194:197], v[50:65]
	global_load_lds_dwordx4 v170, s[20:21]
	s_add_u32 m0, s24, 0xe000
	v_mfma_f32_32x32x16_bf16 v[2:17], v[154:157], v[198:201], v[2:17]
	global_load_lds_dwordx4 v170, s[14:15]
	s_add_u32 m0, s24, 0x1e000
	v_mfma_f32_32x32x16_bf16 v[34:49], v[158:161], v[198:201], v[34:49]
	global_load_lds_dwordx4 v170, s[22:23]
.Lg_mlp2_mid:
	ds_read_b128 v[154:157], v185
	ds_read_b128 v[162:165], v181
	ds_read_b128 v[158:161], v185 offset:4096
	ds_read_b128 v[166:169], v181 offset:4096
	ds_read_b128 v[194:197], v181 offset:8192
	ds_read_b128 v[198:201], v181 offset:12288
	s_waitcnt lgkmcnt(6)
	v_mfma_f32_32x32x16_bf16 v[66:81], v[130:133], v[138:141], v[66:81]
	s_add_u32 s8, s8, 0x80
	s_addc_u32 s9, s9, 0
	v_mfma_f32_32x32x16_bf16 v[114:129], v[134:137], v[138:141], v[114:129]
	s_add_u32 s10, s10, 0x80
	s_addc_u32 s11, s11, 0
	v_mfma_f32_32x32x16_bf16 v[82:97], v[130:133], v[142:145], v[82:97]
	s_add_u32 s12, s12, 0x80
	s_addc_u32 s13, s13, 0
	v_mfma_f32_32x32x16_bf16 v[98:113], v[134:137], v[142:145], v[98:113]
	s_add_u32 s14, s14, 0x80
	s_addc_u32 s15, s15, 0
	v_mfma_f32_32x32x16_bf16 v[18:33], v[130:133], v[146:149], v[18:33]
	s_add_u32 s16, s16, 0x80
	s_addc_u32 s17, s17, 0
	v_mfma_f32_32x32x16_bf16 v[50:65], v[134:137], v[146:149], v[50:65]
	s_add_u32 s18, s18, 0x80
	s_addc_u32 s19, s19, 0
	v_mfma_f32_32x32x16_bf16 v[2:17], v[130:133], v[150:153], v[2:17]
	s_add_u32 s20, s20, 0x80
	s_addc_u32 s21, s21, 0
	v_mfma_f32_32x32x16_bf16 v[34:49], v[134:137], v[150:153], v[34:49]
	s_add_u32 s22, s22, 0x80
	s_addc_u32 s23, s23, 0
	ds_read_b128 v[130:133], v186
	ds_read_b128 v[138:141], v182
	ds_read_b128 v[134:137], v186 offset:4096
	ds_read_b128 v[142:145], v182 offset:4096
	ds_read_b128 v[146:149], v182 offset:8192
	ds_read_b128 v[150:153], v182 offset:12288
	s_waitcnt lgkmcnt(6)
	v_mfma_f32_32x32x16_bf16 v[66:81], v[154:157], v[162:165], v[66:81]
	v_mfma_f32_32x32x16_bf16 v[114:129], v[158:161], v[162:165], v[114:129]
	v_mfma_f32_32x32x16_bf16 v[82:97], v[154:157], v[166:169], v[82:97]
	v_mfma_f32_32x32x16_bf16 v[98:113], v[158:161], v[166:169], v[98:113]
	v_mfma_f32_32x32x16_bf16 v[18:33], v[154:157], v[194:197], v[18:33]
	v_mfma_f32_32x32x16_bf16 v[50:65], v[158:161], v[194:197], v[50:65]
	v_mfma_f32_32x32x16_bf16 v[2:17], v[154:157], v[198:201], v[2:17]
	v_mfma_f32_32x32x16_bf16 v[34:49], v[158:161], v[198:201], v[34:49]
	ds_read_b128 v[154:157], v187
	ds_read_b128 v[162:165], v183
	ds_read_b128 v[158:161], v187 offset:4096
	ds_read_b128 v[166:169], v183 offset:4096
	ds_read_b128 v[194:197], v183 offset:8192
	ds_read_b128 v[198:201], v183 offset:12288
	s_waitcnt lgkmcnt(6)
	v_mfma_f32_32x32x16_bf16 v[66:81], v[130:133], v[138:141], v[66:81]
	v_mfma_f32_32x32x16_bf16 v[114:129], v[134:137], v[138:141], v[114:129]
	v_mfma_f32_32x32x16_bf16 v[82:97], v[130:133], v[142:145], v[82:97]
	v_mfma_f32_32x32x16_bf16 v[98:113], v[134:137], v[142:145], v[98:113]
	v_mfma_f32_32x32x16_bf16 v[18:33], v[130:133], v[146:149], v[18:33]
	v_mfma_f32_32x32x16_bf16 v[50:65], v[134:137], v[146:149], v[50:65]
	v_mfma_f32_32x32x16_bf16 v[2:17], v[130:133], v[150:153], v[2:17]
	v_mfma_f32_32x32x16_bf16 v[34:49], v[134:137], v[150:153], v[34:49]
	s_waitcnt vmcnt(0) lgkmcnt(0)
	s_barrier
	ds_read_b128 v[130:133], v184 offset:32768
	ds_read_b128 v[138:141], v188
	ds_read_b128 v[134:137], v184 offset:36864
	ds_read_b128 v[142:145], v188 offset:4096
	ds_read_b128 v[146:149], v188 offset:8192
	ds_read_b128 v[150:153], v188 offset:12288
	s_cmp_ge_u32 s3, 62
	s_cbranch_scc1 .Lg_mlp2_nodma
	s_add_u32 m0, s24, 0x0
	v_mfma_f32_32x32x16_bf16 v[66:81], v[154:157], v[162:165], v[66:81]
	global_load_lds_dwordx4 v170, s[8:9]
	s_add_u32 m0, s24, 0x10000
	v_mfma_f32_32x32x16_bf16 v[114:129], v[158:161], v[162:165], v[114:129]
	global_load_lds_dwordx4 v170, s[16:17]
	s_add_u32 m0, s24, 0x2000
	v_mfma_f32_32x32x16_bf16 v[82:97], v[154:157], v[166:169], v[82:97]
	global_load_lds_dwordx4 v170, s[10:11]
	s_add_u32 m0, s24, 0x12000
	v_mfma_f32_32x32x16_bf16 v[98:113], v[158:161], v[166:169], v[98:113]
	global_load_lds_dwordx4 v170, s[18:19]
	s_add_u32 m0, s24, 0x4000
	v_mfma_f32_32x32x16_bf16 v[18:33], v[154:157], v[194:197], v[18:33]
	global_load_lds_dwordx4 v170, s[12:13]
	s_add_u32 m0, s24, 0x14000
	v_mfma_f32_32x32x16_bf16 v[50:65], v[158:161], v[194:197], v[50:65]
	global_load_lds_dwordx4 v170, s[20:21]
	s_add_u32 m0, s24, 0x6000
	v_mfma_f32_32x32x16_bf16 v[2:17], v[154:157], v[198:201], v[2:17]
	global_load_lds_dwordx4 v170, s[14:15]
	s_add_u32 m0, s24, 0x16000
	v_mfma_f32_32x32x16_bf16 v[34:49], v[158:161], v[198:201], v[34:49]
	global_load_lds_dwordx4 v170, s[22:23]
	s_branch .Lg_mlp2_join
.Lg_mlp2_nodma:
	v_mfma_f32_32x32x16_bf16 v[66:81], v[154:157], v[162:165], v[66:81]
	v_mfma_f32_32x32x16_bf16 v[114:129], v[158:161], v[162:165], v[114:129]
	v_mfma_f32_32x32x16_bf16 v[82:97], v[154:157], v[166:169], v[82:97]
	v_mfma_f32_32x32x16_bf16 v[98:113], v[158:161], v[166:169], v[98:113]
	v_mfma_f32_32x32x16_bf16 v[18:33], v[154:157], v[194:197], v[18:33]
	v_mfma_f32_32x32x16_bf16 v[50:65], v[158:161], v[194:197], v[50:65]
	v_mfma_f32_32x32x16_bf16 v[2:17], v[154:157], v[198:201], v[2:17]
	v_mfma_f32_32x32x16_bf16 v[34:49], v[158:161], v[198:201], v[34:49]
.Lg_mlp2_join:
	ds_read_b128 v[154:157], v185 offset:32768
	ds_read_b128 v[162:165], v189
	ds_read_b128 v[158:161], v185 offset:36864
	ds_read_b128 v[166:169], v189 offset:4096
	ds_read_b128 v[194:197], v189 offset:8192
	ds_read_b128 v[198:201], v189 offset:12288
	s_waitcnt lgkmcnt(6)
	v_mfma_f32_32x32x16_bf16 v[66:81], v[130:133], v[138:141], v[66:81]
	s_add_u32 s8, s8, 0x80
	s_addc_u32 s9, s9, 0
	v_mfma_f32_32x32x16_bf16 v[114:129], v[134:137], v[138:141], v[114:129]
	s_add_u32 s10, s10, 0x80
	s_addc_u32 s11, s11, 0
	v_mfma_f32_32x32x16_bf16 v[82:97], v[130:133], v[142:145], v[82:97]
	s_add_u32 s12, s12, 0x80
	s_addc_u32 s13, s13, 0
	v_mfma_f32_32x32x16_bf16 v[98:113], v[134:137], v[142:145], v[98:113]
	s_add_u32 s14, s14, 0x80
	s_addc_u32 s15, s15, 0
	v_mfma_f32_32x32x16_bf16 v[18:33], v[130:133], v[146:149], v[18:33]
	s_add_u32 s16, s16, 0x80
	s_addc_u32 s17, s17, 0
	v_mfma_f32_32x32x16_bf16 v[50:65], v[134:137], v[146:149], v[50:65]
	s_add_u32 s18, s18, 0x80
	s_addc_u32 s19, s19, 0
	v_mfma_f32_32x32x16_bf16 v[2:17], v[130:133], v[150:153], v[2:17]
	s_add_u32 s20, s20, 0x80
	s_addc_u32 s21, s21, 0
	v_mfma_f32_32x32x16_bf16 v[34:49], v[134:137], v[150:153], v[34:49]
	s_add_u32 s22, s22, 0x80
	s_addc_u32 s23, s23, 0
	ds_read_b128 v[130:133], v186 offset:32768
	ds_read_b128 v[138:141], v190
	ds_read_b128 v[134:137], v186 offset:36864
	ds_read_b128 v[142:145], v190 offset:4096
	ds_read_b128 v[146:149], v190 offset:8192
	ds_read_b128 v[150:153], v190 offset:12288
	s_waitcnt lgkmcnt(6)
	v_mfma_f32_32x32x16_bf16 v[66:81], v[154:157], v[162:165], v[66:81]
	v_mfma_f32_32x32x16_bf16 v[114:129], v[158:161], v[162:165], v[114:129]
	v_mfma_f32_32x32x16_bf16 v[82:97], v[154:157], v[166:169], v[82:97]
	v_mfma_f32_32x32x16_bf16 v[98:113], v[158:161], v[166:169], v[98:113]
	v_mfma_f32_32x32x16_bf16 v[18:33], v[154:157], v[194:197], v[18:33]
	v_mfma_f32_32x32x16_bf16 v[50:65], v[158:161], v[194:197], v[50:65]
	v_mfma_f32_32x32x16_bf16 v[2:17], v[154:157], v[198:201], v[2:17]
	v_mfma_f32_32x32x16_bf16 v[34:49], v[158:161], v[198:201], v[34:49]
	ds_read_b128 v[154:157], v187 offset:32768
	ds_read_b128 v[162:165], v191
	ds_read_b128 v[158:161], v187 offset:36864
	ds_read_b128 v[166:169], v191 offset:4096
	ds_read_b128 v[194:197], v191 offset:8192
	ds_read_b128 v[198:201], v191 offset:12288
	s_waitcnt lgkmcnt(6)
	v_mfma_f32_32x32x16_bf16 v[66:81], v[130:133], v[138:141], v[66:81]
	v_mfma_f32_32x32x16_bf16 v[114:129], v[134:137], v[138:141], v[114:129]
	v_mfma_f32_32x32x16_bf16 v[82:97], v[130:133], v[142:145], v[82:97]
	v_mfma_f32_32x32x16_bf16 v[98:113], v[134:137], v[142:145], v[98:113]
	v_mfma_f32_32x32x16_bf16 v[18:33], v[130:133], v[146:149], v[18:33]
	v_mfma_f32_32x32x16_bf16 v[50:65], v[134:137], v[146:149], v[50:65]
	v_mfma_f32_32x32x16_bf16 v[2:17], v[130:133], v[150:153], v[2:17]
	v_mfma_f32_32x32x16_bf16 v[34:49], v[134:137], v[150:153], v[34:49]
	s_waitcnt vmcnt(0) lgkmcnt(0)
	s_barrier
	s_add_i32 s3, s3, 2
	s_cmp_lt_u32 s3, 64
	s_cbranch_scc1 .Lg_mlp2_top
	v_mfma_f32_32x32x16_bf16 v[66:81], v[154:157], v[162:165], v[66:81]
	v_mfma_f32_32x32x16_bf16 v[114:129], v[158:161], v[162:165], v[114:129]
	v_mfma_f32_32x32x16_bf16 v[82:97], v[154:157], v[166:169], v[82:97]
	v_mfma_f32_32x32x16_bf16 v[98:113], v[158:161], v[166:169], v[98:113]
	v_mfma_f32_32x32x16_bf16 v[18:33], v[154:157], v[194:197], v[18:33]
	v_mfma_f32_32x32x16_bf16 v[50:65], v[158:161], v[194:197], v[50:65]
	v_mfma_f32_32x32x16_bf16 v[2:17], v[154:157], v[198:201], v[2:17]
	v_mfma_f32_32x32x16_bf16 v[34:49], v[158:161], v[198:201], v[34:49]
	s_nop 7
	s_nop 7
	s_branch .LBB0_1696
